# combination: conv-tile cache + LRU priority scheme + deep-prefetch stage-wise bwd gate segment + carry trims + cl fold
# baseline (speedup 1.0000x reference)
; #define LAS __attribute__((address_space(3)))
; __device__ __forceinline__ int opaque_tid() { int t = threadIdx.x; asm volatile("" : "+v"(t)); return t; }
; #define LDS_BARRIER() do { asm volatile("s_waitcnt lgkmcnt(0)" ::: "memory"); __builtin_amdgcn_s_barrier(); asm volatile("" ::: "memory"); } while (0)
; template <int dir>
; __device__ __forceinline__ void lru_pass(LAS unsigned char* lds, const Params& P, int b, int h, int q, bool dry) {
;     ...
;     const int cgp = tid & 15, tr = tid >> 4;
;     const int s_i = 16 * ((nl >> 2) & 1) + ((nl >> 3) << 2) + (nl & 3);
;     const bf16_t* Zg = Z + ZSLAB(8 + h, (size_t)b * SEQ) + q * 32;
;     unsigned* Hg = HFW + (size_t)b * SEQ * DM + h * 128 + q * 32;
;     {
; #pragma unroll
;         for (int i = 0; i < 2; ++i) { const int idx = tid + i * NTHREADS, gate = idx >> 9, n = (idx >> 4) & 31, kc = idx & 15;
;             *(LAS u32x4*)(WB + (gate * 32 + n) * XC_PITCH + kc * 16) = *(const u32x4*)(LruW + ((size_t)((dir * 2 + gate) * 8 + h) * 128 + q * 32 + n) * 128 + kc * 8); }
;         const float br = -LOG2E * P.lru_ba[(dir * 8 + h) * 128 + chl], bi = -LOG2E * P.lru_bx[(dir * 8 + h) * 128 + chl];
;         const float lam = P.lru_lambda[dir * 1024 + ch];
;         const float cl = -8.0f * LOG2E * log1pf(__expf(-lam));
;         float carry = 0.f;
;         LruTile cur = lru_tile(Z, ZC, b, h, dir, 0);
;         u32x4 rows[11];
;         constexpr int NIN = dir == 0 ? 2 : 4;
;         u32x4 inr[NIN];
;         lru_load_rows(rows, cur, tr, cgp);
; __device__ __forceinline__ void lru_strip(LAS unsigned char* lds, const Params& P, int strip, bool dry) {
;     const int tid = opaque_tid();
;     const int b = strip >> 5, h = (strip >> 2) & 7, q = strip & 3;
;     LAS float* CWL = (LAS float*)(lds + 256 * XC_PITCH + 2048 + 64 * XC_PITCH);
;     for (int i = tid; i < 640; i += NTHREADS) { const int k = i >> 7, c = i & 127; CWL[i] = k < 4 ? P.conv_w[k * 1024 + h * 128 + c] : P.conv_b[h * 128 + c]; }
;     LDS_BARRIER();
;     lru_pass<0>(lds, P, b, h, q, dry);
.LBB0_278:
	s_ashr_i32 s25, s2, 3
	v_mov_b32_e32 v128, v167
	s_bfe_u32 s26, s25, 0x30002
	s_lshl_b32 s27, s26, 7
	v_and_b32_e32 v204, 0x7f, v128
	v_or_b32_e32 v204, s27, v204
	v_lshrrev_b32_e32 v205, 7, v128
	v_lshl_or_b32 v205, v205, 10, v204
	v_lshlrev_b32_e32 v205, 2, v205
	v_lshlrev_b32_e32 v204, 2, v204
	global_load_dword v205, v205, s[52:53]
	global_load_dword v204, v204, s[54:55]
	v_readlane_b32 s0, v255, 19
	s_nop 3
	v_lshl_add_u32 v206, v128, 2, s0
	v_mov_b32_e32 v12, v167
	s_lshl_b32 s0, s25, 5
	s_and_b32 s28, s0, 0x60
	v_and_b32_e32 v15, 31, v12
	v_or_b32_e32 v17, s28, v15
	v_add_u32_e32 v14, 0x200, v12
	v_or_b32_e32 v11, s27, v17
	v_ashrrev_i32_e32 v8, 9, v12
	v_ashrrev_i32_e32 v10, 9, v14
	v_lshlrev_b32_e32 v16, 2, v11
	v_and_b32_e32 v13, 15, v12
	v_lshl_or_b32 v2, v8, 3, s26
	v_lshl_or_b32 v6, v10, 3, s26
	global_load_dword v18, v16, s[64:65]
	v_bfe_u32 v9, v12, 4, 5
	v_lshlrev_b32_e32 v64, 4, v13
	v_ashrrev_i32_e32 v3, 31, v2
	v_ashrrev_i32_e32 v7, 31, v6
	v_or_b32_e32 v4, s28, v9
	v_lshl_add_u64 v[0:1], s[38:39], 0, v[64:65]
	v_lshlrev_b64 v[2:3], 15, v[2:3]
	v_lshlrev_b64 v[6:7], 15, v[6:7]
	v_lshlrev_b32_e32 v4, 8, v4
	v_mov_b32_e32 v5, v65
	v_lshl_add_u64 v[2:3], v[0:1], 0, v[2:3]
	v_lshl_add_u64 v[0:1], v[0:1], 0, v[6:7]
	v_lshl_add_u64 v[2:3], v[2:3], 0, v[4:5]
	v_lshl_add_u64 v[4:5], v[0:1], 0, v[4:5]
	global_load_dwordx4 v[0:3], v[2:3], off
	s_nop 0
	global_load_dwordx4 v[4:7], v[4:5], off
	v_lshlrev_b32_e32 v11, 2, v12
	v_lshl_or_b32 v21, v8, 5, v9
	v_add_u32_e32 v8, s88, v64
	v_lshl_or_b32 v9, v10, 5, v9
	v_and_b32_e32 v22, 16, v11
	v_mad_u64_u32 v[10:11], s[4:5], v21, s89, v[8:9]
	v_mad_u64_u32 v[8:9], s[4:5], v9, s89, v[8:9]
	global_load_dword v9, v16, s[58:59]
	global_load_dword v11, v16, s[62:63]
	s_lshl_b32 s0, s2, 5
	s_and_b32 s0, s0, 0xe0
	s_or_b32 s1, s0, s25
	s_ashr_i32 s78, s1, 5
	s_ashr_i32 s79, s78, 31
	s_lshl_b32 s20, s26, 22
	s_lshl_b64 s[18:19], s[78:79], 19
	s_lshl_b64 s[44:45], s[78:79], 23
	v_readlane_b32 s1, v255, 18
	s_add_u32 s1, s1, s44
	s_addc_u32 s4, s33, s45
	s_lshl_b32 s5, s27, 2
	s_add_u32 s1, s1, s5
	s_addc_u32 s4, s4, 0
	s_add_u32 s5, s68, s18
	s_addc_u32 s6, s69, s19
	s_lshl_b32 s7, s27, 1
	s_add_u32 s48, s5, s7
	s_addc_u32 s49, s6, 0
	s_add_u32 s50, s48, 0x1000
	s_addc_u32 s51, s49, 0
	s_add_u32 s56, s48, 0x1800
	s_addc_u32 s57, s49, 0
	s_add_u32 s60, s48, 0x2000
	s_addc_u32 s61, s49, 0
	s_add_u32 s66, s48, 0x2800
	s_addc_u32 s67, s49, 0
	s_add_u32 s70, s48, 0x3000
	s_addc_u32 s71, s49, 0
	v_ashrrev_i32_e32 v36, 4, v12
	v_lshlrev_b32_e32 v37, 3, v13
	s_add_u32 s72, s48, 0x3800
	s_addc_u32 s73, s49, 0
	s_add_u32 s74, s48, 0x4000
	s_addc_u32 s75, s49, 0
	s_add_u32 s76, s48, 0x4800
	s_addc_u32 s77, s49, 0
	v_readfirstlane_b32 s0, v12
	s_ashr_i32 s6, s0, 6
	s_lshl_b32 s5, s28, 2
	s_add_u32 s8, s1, s5
	v_bfe_u32 v19, v12, 5, 1
	v_lshrrev_b32_e32 v20, 1, v12
	v_and_b32_e32 v33, 3, v12
	s_addc_u32 s9, s4, 0
	v_lshl_or_b32 v110, v36, 13, v37
	v_mov_b32_e32 v111, v65
	v_lshlrev_b64 v[110:111], 1, v[110:111]
	v_lshl_add_u64 v[108:109], s[48:49], 0, v[110:111]
	global_load_dwordx4 v[68:71], v[108:109], off offset:-2048
	global_load_dwordx4 v[72:75], v[108:109], off
	global_load_dwordx4 v[76:79], v[108:109], off offset:2048
	v_lshl_add_u64 v[108:109], s[50:51], 0, v[110:111]
	global_load_dwordx4 v[80:83], v[108:109], off
	v_lshl_add_u64 v[108:109], s[56:57], 0, v[110:111]
	global_load_dwordx4 v[84:87], v[108:109], off
	v_lshl_add_u64 v[108:109], s[60:61], 0, v[110:111]
	global_load_dwordx4 v[88:91], v[108:109], off
	v_lshl_add_u64 v[108:109], s[66:67], 0, v[110:111]
	global_load_dwordx4 v[92:95], v[108:109], off
	v_lshl_add_u64 v[108:109], s[70:71], 0, v[110:111]
	global_load_dwordx4 v[96:99], v[108:109], off
	v_lshl_add_u64 v[108:109], s[72:73], 0, v[110:111]
	global_load_dwordx4 v[100:103], v[108:109], off
	v_lshl_add_u64 v[108:109], s[74:75], 0, v[110:111]
	global_load_dwordx4 v[104:107], v[108:109], off
	v_lshl_add_u64 v[108:109], s[76:77], 0, v[110:111]
	global_load_dwordx4 v[108:111], v[108:109], off
	s_waitcnt vmcnt(14)
	ds_write_b128 v10, v[0:3]
	s_waitcnt vmcnt(13)
	ds_write_b128 v8, v[4:7]
	ds_write_b32 v206, v205
	v_cmp_gt_u32_e32 vcc, 0x80, v128
	s_and_saveexec_b64 s[14:15], vcc
	ds_write_b32 v206, v204 offset:2048
	s_or_b64 exec, exec, s[14:15]
	v_mul_f32_e32 v16, 0xbfb8aa3b, v18
	v_exp_f32_e32 v16, v16
	s_lshl_b32 s1, s6, 5
	s_and_b32 s0, s0, 0x3fffffc0
	v_add_u32_e32 v39, 0, v64
	v_add_f32_e32 v2, 1.0, v16
	v_add_f32_e32 v3, -1.0, v2
	v_frexp_mant_f32_e32 v4, v2
	v_cvt_f64_f32_e32 v[0:1], v2
	v_sub_f32_e32 v5, v3, v2
	v_frexp_exp_i32_f64_e32 v0, v[0:1]
	v_cmp_gt_f32_e32 vcc, s80, v4
	v_sub_f32_e32 v3, v16, v3
	v_add_f32_e32 v1, 1.0, v5
	v_subbrev_co_u32_e32 v0, vcc, 0, v0, vcc
	v_add_f32_e32 v1, v3, v1
	v_sub_u32_e32 v3, 0, v0
	v_ldexp_f32 v2, v2, v3
	v_ldexp_f32 v1, v1, v3
	v_add_f32_e32 v3, -1.0, v2
	v_add_f32_e32 v4, 1.0, v2
	v_add_f32_e32 v5, 1.0, v3
	v_add_f32_e32 v6, -1.0, v4
	v_sub_f32_e32 v5, v2, v5
	v_sub_f32_e32 v2, v2, v6
	v_add_f32_e32 v5, v1, v5
	v_add_f32_e32 v1, v1, v2
	v_add_f32_e32 v6, v4, v1
	v_rcp_f32_e32 v7, v6
	v_add_f32_e32 v2, v3, v5
	v_sub_f32_e32 v4, v6, v4
	v_sub_f32_e32 v3, v2, v3
	v_sub_f32_e32 v1, v1, v4
	v_mul_f32_e32 v4, v2, v7
	v_sub_f32_e32 v3, v5, v3
	v_mul_f32_e32 v5, v6, v4
	v_fma_f32 v8, v4, v6, -v5
	v_fmac_f32_e32 v8, v4, v1
	v_add_f32_e32 v10, v5, v8
	v_sub_f32_e32 v18, v2, v10
	v_sub_f32_e32 v2, v2, v18
	v_sub_f32_e32 v5, v10, v5
	v_sub_f32_e32 v2, v2, v10
	v_sub_f32_e32 v5, v5, v8
	v_add_f32_e32 v2, v3, v2
	v_add_f32_e32 v2, v5, v2
	v_add_f32_e32 v3, v18, v2
	v_mul_f32_e32 v5, v7, v3
	v_mul_f32_e32 v10, v6, v5
	v_fma_f32 v6, v5, v6, -v10
; #define LAS __attribute__((address_space(3)))
; template <int dir>
; __device__ __forceinline__ void lru_pass(LAS unsigned char* lds, const Params& P, int b, int h, int q, bool dry) {
;     ...
;     {
; #pragma unroll
;         for (int i = 0; i < 2; ++i) { const int idx = tid + i * NTHREADS, gate = idx >> 9, n = (idx >> 4) & 31, kc = idx & 15;
;             *(LAS u32x4*)(WB + (gate * 32 + n) * XC_PITCH + kc * 16) = *(const u32x4*)(LruW + ((size_t)((dir * 2 + gate) * 8 + h) * 128 + q * 32 + n) * 128 + kc * 8); }
;         const float br = -LOG2E * P.lru_ba[(dir * 8 + h) * 128 + chl], bi = -LOG2E * P.lru_bx[(dir * 8 + h) * 128 + chl];
;         const float lam = P.lru_lambda[dir * 1024 + ch];
;         const float cl = -8.0f * LOG2E * log1pf(__expf(-lam));
;         float carry = 0.f;
;         LruTile cur = lru_tile(Z, ZC, b, h, dir, 0);
;         u32x4 rows[11];
;         constexpr int NIN = dir == 0 ? 2 : 4;
;         u32x4 inr[NIN];
;         lru_load_rows(rows, cur, tr, cgp);
; #pragma unroll
;         for (int i = 0; i < NIN; ++i) inr[i] = (u32x4){0u, 0u, 0u, 0u};
;         int t0_prev = 0;
	v_fmac_f32_e32 v6, v5, v1
	v_add_f32_e32 v1, v10, v6
	v_sub_f32_e32 v8, v18, v3
	v_sub_f32_e32 v18, v3, v1
	v_sub_f32_e32 v3, v3, v18
	v_add_f32_e32 v2, v2, v8
	v_sub_f32_e32 v10, v1, v10
	v_sub_f32_e32 v1, v3, v1
	v_sub_f32_e32 v6, v10, v6
	v_add_f32_e32 v1, v2, v1
	v_cvt_f32_i32_e32 v0, v0
	v_add_f32_e32 v8, v4, v5
	v_add_f32_e32 v1, v6, v1
	v_add_f32_e32 v1, v18, v1
	v_sub_f32_e32 v2, v8, v4
	v_mul_f32_e32 v1, v7, v1
	v_sub_f32_e32 v2, v5, v2
	v_add_f32_e32 v1, v2, v1
	v_mul_f32_e32 v5, 0x3f317218, v0
	v_add_f32_e32 v2, v8, v1
	v_fma_f32 v6, v0, s81, -v5
	v_fmac_f32_e32 v6, 0xb102e308, v0
	v_sub_f32_e32 v0, v2, v8
	v_mul_f32_e32 v3, v2, v2
	v_sub_f32_e32 v0, v1, v0
	v_add_f32_e32 v1, v5, v6
	v_fmamk_f32 v4, v3, 0x3e9b6dac, v200
	v_sub_f32_e32 v5, v1, v5
	v_fmaak_f32 v4, v3, v4, 0x3f2aaada
	v_sub_f32_e32 v5, v6, v5
	v_ldexp_f32 v6, v2, 1
	v_mul_f32_e32 v2, v2, v3
	v_mul_f32_e32 v2, v2, v4
	v_add_f32_e32 v3, v6, v2
	v_sub_f32_e32 v4, v3, v6
	v_ldexp_f32 v0, v0, 1
	v_sub_f32_e32 v2, v2, v4
	v_add_f32_e32 v0, v0, v2
	v_add_f32_e32 v2, v3, v0
	v_sub_f32_e32 v3, v2, v3
	v_sub_f32_e32 v0, v0, v3
	v_add_f32_e32 v3, v1, v2
	v_sub_f32_e32 v4, v3, v1
	v_sub_f32_e32 v6, v3, v4
	v_sub_f32_e32 v1, v1, v6
	v_sub_f32_e32 v2, v2, v4
	v_add_f32_e32 v1, v2, v1
	v_add_f32_e32 v2, v5, v0
	v_sub_f32_e32 v4, v2, v5
	v_add_f32_e32 v1, v2, v1
	v_sub_f32_e32 v6, v2, v4
	v_add_f32_e32 v2, v3, v1
	v_sub_f32_e32 v5, v5, v6
	v_sub_f32_e32 v0, v0, v4
	v_sub_f32_e32 v3, v2, v3
	v_add_f32_e32 v0, v0, v5
	v_sub_f32_e32 v1, v1, v3
	v_add_f32_e32 v0, v0, v1
	v_add_f32_e32 v0, v2, v0
	v_cmp_neq_f32_e32 vcc, s91, v16
	v_mov_b32_e32 v1, v65
	v_lshlrev_b32_e32 v41, 4, v19
	v_cndmask_b32_e32 v0, v201, v0, vcc
	v_cmp_ngt_f32_e32 vcc, -1.0, v16
	s_cmp_eq_u32 s6, 7
	v_or_b32_e32 v35, s1, v41
	v_cndmask_b32_e32 v0, v202, v0, vcc
	v_cmp_neq_f32_e32 vcc, -1.0, v16
	v_ashrrev_i32_e32 v32, 2, v12
	v_ashrrev_i32_e32 v34, 2, v14
	v_cndmask_b32_e32 v0, v203, v0, vcc
	v_cmp_lt_f32_e64 vcc, |v16|, s92
	v_lshlrev_b32_e32 v53, 4, v33
	v_mul_lo_u32 v48, v32, s87
	v_cndmask_b32_e32 v6, v0, v16, vcc
	v_lshlrev_b32_e32 v1, 2, v15
	v_lshlrev_b32_e32 v2, 4, v12
	v_add_u32_e32 v140, s94, v1
	v_and_b32_e32 v3, 48, v2
	v_and_b32_e32 v64, 0x70, v2
	v_and_or_b32 v2, v20, 12, v33
	v_or3_b32 v2, v2, v22, s1
	v_lshl_add_u32 v147, s0, 2, v140
	s_cselect_b64 s[0:1], -1, 0
	s_cmp_eq_u32 s6, 6
	s_cselect_b64 s[16:17], -1, 0
	s_cmp_eq_u32 s6, 5
	s_cselect_b64 s[4:5], -1, 0
	s_cmp_eq_u32 s6, 4
	v_lshl_add_u64 v[130:131], s[8:9], 0, v[64:65]
	s_cselect_b64 s[8:9], -1, 0
	s_cmp_eq_u32 s6, 3
	s_cselect_b64 s[10:11], -1, 0
	s_cmp_eq_u32 s6, 2
	s_cselect_b64 s[12:13], -1, 0
	s_cmp_eq_u32 s6, 1
	s_cselect_b64 s[14:15], -1, 0
	s_add_u32 s46, s20, s18
	s_addc_u32 s47, 0, s19
	s_lshl_b32 s6, s2, 3
	v_ashrrev_i32_e32 v33, 31, v32
	v_mul_lo_u32 v50, v35, s89
	v_mul_lo_u32 v51, v35, s87
	v_mul_lo_u32 v52, v35, s30
	v_ashrrev_i32_e32 v35, 31, v34
	s_bfe_u32 s29, s2, 0x20003
	s_and_b32 s6, s6, 0xc0
	v_lshlrev_b64 v[32:33], 8, v[32:33]
	v_mul_lo_u32 v2, v2, s89
	v_add_u32_e32 v46, s96, v1
	v_mul_lo_u32 v49, v34, s87
	v_add_u32_e32 v1, 0x400, v12
	v_lshlrev_b64 v[34:35], 8, v[34:35]
	v_lshl_add_u64 v[32:33], s[46:47], 0, v[32:33]
	s_add_u32 s18, s82, s46
	v_lshlrev_b32_e32 v38, 5, v13
	v_add_u32_e32 v129, s96, v64
	v_add_u32_e32 v42, 0, v2
	v_mov_b32_e32 v2, s88
	v_ashrrev_i32_e32 v143, 3, v1
	v_add_u32_e32 v1, 0x600, v12
	v_lshl_add_u64 v[34:35], s[46:47], 0, v[34:35]
	v_or3_b32 v32, v32, s6, v53
	v_lshl_or_b32 v64, v36, 10, v37
	s_addc_u32 s19, s83, s47
	v_mov_b32_e32 v66, v65
	v_mov_b32_e32 v67, v65
	s_waitcnt vmcnt(12)
	v_mul_f32_e32 v0, 0xbfb8aa3b, v9
	s_waitcnt vmcnt(11)
; template <int dir>
; __device__ __forceinline__ void lru_pass(LAS unsigned char* lds, const Params& P, int b, int h, int q, bool dry) {
;     ...
;         const float br = -LOG2E * P.lru_ba[(dir * 8 + h) * 128 + chl], bi = -LOG2E * P.lru_bx[(dir * 8 + h) * 128 + chl];
;         const float lam = P.lru_lambda[dir * 1024 + ch];
;         const float cl = -8.0f * LOG2E * log1pf(__expf(-lam));
;         float carry = 0.f;
;         LruTile cur = lru_tile(Z, ZC, b, h, dir, 0);
;         u32x4 rows[11];
;         constexpr int NIN = dir == 0 ? 2 : 4;
;         u32x4 inr[NIN];
;         lru_load_rows(rows, cur, tr, cgp);
; #pragma unroll
;         for (int i = 0; i < NIN; ++i) inr[i] = (u32x4){0u, 0u, 0u, 0u};
;         int t0_prev = 0;
;     ...
;             f32x16 zr, zi;
; #pragma unroll
;             for (int v = 0; v < 16; ++v) { zr[v] = br; zi[v] = bi; }
;             const int sbase = 32 * wid + 16 * g;
	v_mul_f32_e32 v16, 0xbfb8aa3b, v11
	v_add_u32_e32 v40, s95, v3
	v_mad_u32_u24 v43, v15, s89, v2
	v_lshl_add_u32 v44, v17, 1, 0
	v_lshl_add_u32 v45, v15, 1, s95
	v_mul_lo_u32 v47, v36, s93
	v_ashrrev_i32_e32 v148, 3, v12
	v_ashrrev_i32_e32 v145, 3, v14
	v_ashrrev_i32_e32 v141, 3, v1
	v_or3_b32 v34, v34, s6, v53
	v_lshl_add_u64 v[134:135], s[40:41], 0, v[32:33]
	v_lshl_add_u64 v[136:137], v[64:65], 1, s[18:19]
	v_mov_b32_e32 v64, v65
	v_add_u32_e32 v32, 0, v38
	v_mov_b64_e32 v[114:115], v[66:67]
	v_mov_b64_e32 v[118:119], v[66:67]
	s_mov_b32 s90, 0
	v_mul_f32_e32 v138, 0xc138aa3b, v6
	v_rcp_f32_e32 v138, v138
	s_nop 0
	v_lshl_add_u32 v139, v36, 3, -1
	v_cmp_eq_u32_e32 vcc, 0, v19
	v_mul_lo_u32 v149, v148, s30
	v_mul_lo_u32 v146, v145, s30
	v_mul_lo_u32 v144, v143, s30
	v_mul_lo_u32 v142, v141, s30
	v_mov_b32_e32 v1, v0
	v_mov_b32_e32 v2, v0
	v_mov_b32_e32 v3, v0
	v_mov_b32_e32 v4, v0
	v_mov_b32_e32 v5, v0
	v_mov_b32_e32 v6, v0
	v_mov_b32_e32 v7, v0
	v_mov_b32_e32 v8, v0
	v_mov_b32_e32 v9, v0
	v_mov_b32_e32 v10, v0
	v_mov_b32_e32 v11, v0
	v_mov_b32_e32 v12, v0
	v_mov_b32_e32 v13, v0
	v_mov_b32_e32 v14, v0
	v_mov_b32_e32 v15, v0
	v_mov_b32_e32 v17, v16
	v_mov_b32_e32 v18, v16
	v_mov_b32_e32 v19, v16
	v_mov_b32_e32 v20, v16
	v_mov_b32_e32 v21, v16
	v_mov_b32_e32 v22, v16
	v_mov_b32_e32 v23, v16
	v_mov_b32_e32 v24, v16
	v_mov_b32_e32 v25, v16
	v_mov_b32_e32 v26, v16
	v_mov_b32_e32 v27, v16
	v_mov_b32_e32 v28, v16
	v_mov_b32_e32 v29, v16
	v_mov_b32_e32 v30, v16
	v_mov_b32_e32 v31, v16
	v_lshl_add_u64 v[132:133], s[40:41], 0, v[34:35]
	s_movk_i32 s92, 0x100
	v_mov_b32_e32 v165, 0
	s_mov_b64 s[80:81], 0
	v_add_u32_e32 v150, 0x15c00, v32
	v_add_u32_e32 v151, v39, v47
	v_add_u32_e32 v158, v40, v48
	v_add_u32_e32 v159, v40, v49
	v_add_u32_e32 v160, v42, v41
	v_add_u32_e32 v161, v43, v41
	v_add_u32_e32 v162, v44, v50
	v_add_u32_e32 v163, v45, v51
	v_add_u32_e32 v164, v46, v52
	v_mov_b64_e32 v[112:113], v[64:65]
	v_mov_b64_e32 v[116:117], v[64:65]
	s_mov_b32 s91, 0
	s_mov_b32 s93, 0
	s_mov_b32 s97, 0
	v_lshrrev_b32_e32 v254, 8, v167
	v_mul_u32_u24_e32 v252, 0x1400, v254
	v_add_u32_e32 v158, v158, v252
	v_add_u32_e32 v159, v159, v252
	v_add_u32_e32 v159, 0xffffec00, v159
	v_lshlrev_b32_e32 v252, 14, v254
	v_mov_b32_e32 v253, 0
	v_lshl_add_u64 v[134:135], v[252:253], 0, v[134:135]
	v_lshl_add_u64 v[132:133], v[252:253], 0, v[132:133]
	s_mov_b32 s18, 0xffffc000
	s_mov_b32 s19, -1
	v_lshl_add_u64 v[132:133], v[132:133], 0, s[18:19]
	v_mul_u32_u24_e32 v252, 0x3600, v254
	v_add_u32_e32 v149, v149, v252
	v_add_u32_e32 v146, v146, v252
	v_add_u32_e32 v144, v144, v252
	v_add_u32_e32 v142, v142, v252
	v_add_u32_e32 v146, 0xffffee00, v146
	v_add_u32_e32 v144, 0xffffdc00, v144
	v_add_u32_e32 v142, 0xffffca00, v142
	v_mul_u32_u24_e32 v252, 0x60, v254
	v_add_u32_e32 v148, v148, v252
	v_add_u32_e32 v145, v145, v252
	v_add_u32_e32 v143, v143, v252
	v_add_u32_e32 v141, v141, v252
	v_add_u32_e32 v145, 0xffffffe0, v145
	v_add_u32_e32 v143, 0xffffffc0, v143
	v_add_u32_e32 v141, 0xffffffa0, v141
	v_lshrrev_b32_e32 v253, 6, v167
	s_nop 1
	v_readfirstlane_b32 s18, v253
	s_lshr_b32 s101, s18, 2
	s_or_b32 s19, s18, 4
	s_cmp_eq_u32 s19, 7
	s_cselect_b64 s[0:1], -1, 0
	s_cmp_eq_u32 s19, 6
	s_cselect_b64 s[16:17], -1, 0
	s_cmp_eq_u32 s19, 5
	s_cselect_b64 s[4:5], -1, 0
	s_cmp_eq_u32 s19, 4
	s_cselect_b64 s[8:9], -1, 0
	s_mov_b64 s[10:11], 0
	s_mov_b64 s[12:13], 0
	s_mov_b64 s[14:15], 0
	s_bfe_u32 s42, s2, 0x20003
	s_mov_b32 s98, 0
	s_cmp_eq_u32 s101, 0
	s_cselect_b32 s99, 0x14400, 0
	s_cselect_b32 s100, 0, 0x400
	v_add_u32_e32 v253, 0x14000, v147
	v_mov_b32_e32 v254, 1.0
	v_mov_b32_e32 v252, 0
	ds_write2_b32 v253, v254, v252 offset1:32
	s_waitcnt lgkmcnt(0)
	s_barrier
	s_cmp_eq_u32 s101, 0
	s_cbranch_scc1 .Lpp_f_nox
	s_barrier

; #define LAS __attribute__((address_space(3)))
; template <int dir>
; __device__ __forceinline__ void lru_pass(LAS unsigned char* lds, const Params& P, int b, int h, int q, bool dry) {
;     ...
;             const int sbase = 32 * wid + 16 * g;
;             { const int sl = 32 * wid + s_i; const int tlA = dir == 0 ? sl : 255 - sl;
;               const LAS unsigned char* ap = XC + tlA * XC_PITCH + 16 * g;
;               const LAS unsigned char* wrp = WB + nl * XC_PITCH + 16 * g; const LAS unsigned char* wip = wrp + 32 * XC_PITCH;
; #pragma unroll
;               for (int ks = 0; ks < 8; ++ks) { const bf16x8 A = *(const LAS bf16x8*)(ap + 32 * ks);
;                   const bf16x8 Br = *(const LAS bf16x8*)(wrp + 32 * ks), Bi = *(const LAS bf16x8*)(wip + 32 * ks);
;                   zr = __builtin_amdgcn_mfma_f32_32x32x16_bf16(A, Br, zr, 0, 0, 0); zi = __builtin_amdgcn_mfma_f32_32x32x16_bf16(A, Bi, zi, 0, 0, 0); } }
;             unsigned xcb[16], pk[16];
; #pragma unroll
;             for (int v = 0; v < 16; ++v) { const int s = sbase + v; const int tl = dir == 0 ? s : 255 - s; xcb[v] = *(const LAS bf16_t*)(XC + tl * XC_PITCH + chl * 2);
;                 if (dir == 0) pk[v] = *(const LAS bf16_t*)(TIN + tl * IO_NP + nl * 2); else pk[v] = *(const LAS unsigned*)(TIN + tl * IO_WP + nl * 4); }
;             float Pp = 1.f, E = 0.f;
; #pragma unroll
;             for (int v = 0; v < 16; ++v) {
;                 const float xcv = __uint_as_float(xcb[v] << 16);
;                 const float r = __builtin_amdgcn_rcpf(1.0f + __builtin_amdgcn_exp2f(zr[v]));
;                 const float ig = __builtin_amdgcn_rcpf(1.0f + __builtin_amdgcn_exp2f(zi[v]));
;                 const float a = __builtin_amdgcn_exp2f(cl * r);
;                 const float sq = __builtin_amdgcn_sqrtf(fmaf(-a, a, 1.0f));
;                 const float u = sq * ig * xcv;
;                 E = fmaf(a, E, u); Pp *= a; zr[v] = E; zi[v] = Pp; }
.Llruf_wres:
	ds_read_b128 v[120:123], v160
	ds_read_b128 v[124:127], v160 offset:32
	ds_read_b128 v[168:171], v160 offset:64
	ds_read_b128 v[172:175], v160 offset:96
	ds_read_b128 v[176:179], v160 offset:128
	ds_read_b128 v[180:183], v160 offset:160
	ds_read_b128 v[184:187], v160 offset:192
	ds_read_b128 v[188:191], v160 offset:224
	ds_read_b128 v[236:239], v161 offset:8704
	ds_read_b128 v[240:243], v161 offset:8736
	ds_read_b128 v[244:247], v161 offset:8768
	ds_read_b128 v[248:251], v161 offset:8800
	s_waitcnt lgkmcnt(11)
	v_mfma_f32_32x32x16_bf16 v[32:47], v[120:123], v[204:207], v[0:15]
	s_waitcnt lgkmcnt(10)
	v_mfma_f32_32x32x16_bf16 v[32:47], v[124:127], v[208:211], v[32:47]
	s_waitcnt lgkmcnt(9)
	v_mfma_f32_32x32x16_bf16 v[32:47], v[168:171], v[212:215], v[32:47]
	s_waitcnt lgkmcnt(8)
	v_mfma_f32_32x32x16_bf16 v[32:47], v[172:175], v[216:219], v[32:47]
	s_waitcnt lgkmcnt(7)
	v_mfma_f32_32x32x16_bf16 v[32:47], v[176:179], v[220:223], v[32:47]
	s_waitcnt lgkmcnt(6)
	v_mfma_f32_32x32x16_bf16 v[32:47], v[180:183], v[224:227], v[32:47]
	s_waitcnt lgkmcnt(5)
	v_mfma_f32_32x32x16_bf16 v[32:47], v[184:187], v[228:231], v[32:47]
	s_waitcnt lgkmcnt(4)
	v_mfma_f32_32x32x16_bf16 v[32:47], v[188:191], v[232:235], v[32:47]
	s_waitcnt lgkmcnt(3)
	v_mfma_f32_32x32x16_bf16 v[48:63], v[120:123], v[236:239], v[16:31]
	ds_read_b128 v[236:239], v161 offset:8832
	s_nop 8
	v_exp_f32_e32 v32, v32
	v_exp_f32_e32 v33, v33
	v_exp_f32_e32 v34, v34
	v_fma_f32 v32, v32, v138, v138
	v_rcp_f32_e32 v32, v32
	s_waitcnt lgkmcnt(3)
	v_mfma_f32_32x32x16_bf16 v[48:63], v[124:127], v[240:243], v[48:63]
	ds_read_b128 v[240:243], v161 offset:8864
	v_fma_f32 v33, v33, v138, v138
	v_rcp_f32_e32 v33, v33
	s_nop 0
	s_waitcnt lgkmcnt(3)
	v_mfma_f32_32x32x16_bf16 v[48:63], v[168:171], v[244:247], v[48:63]
	ds_read_b128 v[244:247], v161 offset:8896
	v_exp_f32_e32 v33, v33
	s_waitcnt lgkmcnt(3)
	v_mfma_f32_32x32x16_bf16 v[48:63], v[172:175], v[248:251], v[48:63]
	ds_read_b128 v[248:251], v161 offset:8928
	ds_read_u16 v152, v162
	ds_read_u16 v154, v162 offset:272
	ds_read_u16 v155, v162 offset:544
	ds_read_u16 v157, v162 offset:816
	ds_read_u16 v196, v162 offset:1088
	ds_read_u16 v197, v162 offset:1360
	s_waitcnt lgkmcnt(5)
	v_lshlrev_b32_e32 v152, 16, v152
	s_waitcnt lgkmcnt(4)
	v_lshlrev_b32_e32 v154, 16, v154
	v_mfma_f32_32x32x16_bf16 v[48:63], v[176:179], v[236:239], v[48:63]
	ds_read_u16 v177, v162 offset:1632
	ds_read_u16 v178, v162 offset:1904
	ds_read_u16 v127, v163
	ds_read_u16 v124, v163 offset:80
	ds_read_u16 v121, v163 offset:160
	ds_read_u16 v66, v163 offset:240
	ds_read_u16 v64, v163 offset:320
	ds_read_u16 v126, v163 offset:400
	ds_read_u16 v123, v163 offset:480
	ds_read_u16 v120, v163 offset:560
	v_mfma_f32_32x32x16_bf16 v[48:63], v[180:183], v[240:243], v[48:63]
	v_exp_f32_e32 v171, v32
	ds_read_u16 v179, v162 offset:2176
	ds_read_u16 v180, v162 offset:2448
	ds_read_u16 v181, v162 offset:2720
	v_mfma_f32_32x32x16_bf16 v[48:63], v[184:187], v[244:247], v[48:63]
	ds_read_u16 v182, v162 offset:2992
	ds_read_u16 v183, v162 offset:3264
	ds_read_u16 v184, v162 offset:3536
	ds_read_u16 v185, v162 offset:3808
	ds_read_u16 v187, v162 offset:4080
	v_mfma_f32_32x32x16_bf16 v[48:63], v[188:191], v[248:251], v[48:63]
	s_nop 11
	v_exp_f32_e32 v172, v48
	ds_read_u16 v170, v163 offset:640
	ds_read_u16 v169, v163 offset:720
	ds_read_u16 v168, v163 offset:800
	ds_read_u16 v166, v163 offset:880
	ds_read_u16 v125, v163 offset:960
	ds_read_u16 v122, v163 offset:1040
	ds_read_u16 v67, v163 offset:1120
	ds_read_u16 v48, v163 offset:1200
	v_add_f32_e32 v32, 1.0, v172
	v_fma_f32 v172, -v171, v171, 1.0
	v_rcp_f32_e32 v32, v32
	v_sqrt_f32_e32 v172, v172
	s_nop 0
	v_mul_f32_e32 v32, v172, v32
	v_exp_f32_e32 v172, v49
	v_mul_f32_e32 v49, v32, v152
	v_fma_f32 v152, -v33, v33, 1.0
	v_sqrt_f32_e32 v152, v152
	v_add_f32_e32 v32, 1.0, v172
	v_rcp_f32_e32 v32, v32
	v_fmac_f32_e32 v49, 0, v171
	v_mul_f32_e32 v32, v152, v32
	v_mul_f32_e32 v172, v32, v154
	v_fma_f32 v32, v34, v138, v138
	v_rcp_f32_e32 v32, v32
	v_exp_f32_e32 v34, v50
	v_fmac_f32_e32 v172, v33, v49
	v_mul_f32_e32 v50, v171, v33
	v_exp_f32_e32 v32, v32
	v_add_f32_e32 v33, 1.0, v34
	v_exp_f32_e32 v34, v35
	v_rcp_f32_e32 v33, v33
	v_fma_f32 v35, -v32, v32, 1.0
	v_sqrt_f32_e32 v35, v35
	v_fma_f32 v34, v34, v138, v138
	v_rcp_f32_e32 v34, v34
	s_waitcnt lgkmcnt(14)
; template <int dir>
; __device__ __forceinline__ void lru_pass(LAS unsigned char* lds, const Params& P, int b, int h, int q, bool dry) {
;     ...
;             for (int v = 0; v < 16; ++v) {
;                 const float xcv = __uint_as_float(xcb[v] << 16);
;                 const float r = __builtin_amdgcn_rcpf(1.0f + __builtin_amdgcn_exp2f(zr[v]));
;                 const float ig = __builtin_amdgcn_rcpf(1.0f + __builtin_amdgcn_exp2f(zi[v]));
;                 const float a = __builtin_amdgcn_exp2f(cl * r);
;                 const float sq = __builtin_amdgcn_sqrtf(fmaf(-a, a, 1.0f));
;                 const float u = sq * ig * xcv;
;                 E = fmaf(a, E, u); Pp *= a; zr[v] = E; zi[v] = Pp; }
;             const float Po = __shfl_xor(Pp, 32), Eo = __shfl_xor(E, 32);
;             const float P0 = g ? Po : Pp, E0 = g ? Eo : E, P1 = g ? Pp : Po, E1 = g ? E : Eo;
;             if (g == 0) { AGG[(wid * 2 + 0) * 32 + nl] = P0 * P1; AGG[(wid * 2 + 1) * 32 + nl] = fmaf(P1, E0, E1); }
	v_lshlrev_b32_e32 v152, 16, v155
	v_mul_f32_e32 v33, v35, v33
	v_mul_f32_e32 v173, v33, v152
	v_exp_f32_e32 v33, v51
	v_exp_f32_e32 v34, v34
	v_fmac_f32_e32 v173, v32, v172
	v_mul_f32_e32 v51, v32, v50
	v_exp_f32_e32 v32, v36
	v_add_f32_e32 v33, 1.0, v33
	v_fma_f32 v35, -v34, v34, 1.0
	v_rcp_f32_e32 v33, v33
	v_sqrt_f32_e32 v35, v35
	v_fma_f32 v32, v32, v138, v138
	v_rcp_f32_e32 v32, v32
	v_lshlrev_b32_e32 v36, 16, v157
	v_mul_f32_e32 v33, v35, v33
	v_mul_f32_e32 v174, v33, v36
	v_fmac_f32_e32 v174, v34, v173
	v_exp_f32_e32 v33, v52
	v_mul_f32_e32 v52, v34, v51
	v_exp_f32_e32 v32, v32
	v_exp_f32_e32 v34, v37
	v_add_f32_e32 v33, 1.0, v33
	v_rcp_f32_e32 v33, v33
	v_fma_f32 v35, -v32, v32, 1.0
	v_fma_f32 v34, v34, v138, v138
	v_sqrt_f32_e32 v35, v35
	v_rcp_f32_e32 v34, v34
	v_lshlrev_b32_e32 v36, 16, v196
	v_mul_f32_e32 v33, v35, v33
	v_mul_f32_e32 v175, v33, v36
	v_exp_f32_e32 v33, v53
	v_exp_f32_e32 v34, v34
	v_fmac_f32_e32 v175, v32, v174
	v_mul_f32_e32 v53, v32, v52
	v_exp_f32_e32 v32, v38
	v_add_f32_e32 v33, 1.0, v33
	v_fma_f32 v35, -v34, v34, 1.0
	v_rcp_f32_e32 v33, v33
	v_sqrt_f32_e32 v35, v35
	v_fma_f32 v32, v32, v138, v138
	v_rcp_f32_e32 v32, v32
	v_lshlrev_b32_e32 v36, 16, v197
	v_mul_f32_e32 v33, v35, v33
	v_mul_f32_e32 v176, v33, v36
	v_fmac_f32_e32 v176, v34, v175
	v_exp_f32_e32 v33, v54
	v_mul_f32_e32 v54, v34, v53
	v_exp_f32_e32 v32, v32
	v_exp_f32_e32 v34, v39
	v_add_f32_e32 v33, 1.0, v33
	v_rcp_f32_e32 v33, v33
	v_fma_f32 v35, -v32, v32, 1.0
	v_fma_f32 v34, v34, v138, v138
	v_sqrt_f32_e32 v35, v35
	v_rcp_f32_e32 v34, v34
	v_lshlrev_b32_e32 v36, 16, v177
	v_mul_f32_e32 v33, v35, v33
	v_mul_f32_e32 v177, v33, v36
	v_exp_f32_e32 v33, v55
	v_exp_f32_e32 v34, v34
	v_fmac_f32_e32 v177, v32, v176
	v_mul_f32_e32 v55, v32, v54
	v_exp_f32_e32 v32, v40
	v_add_f32_e32 v33, 1.0, v33
	v_fma_f32 v35, -v34, v34, 1.0
	v_rcp_f32_e32 v33, v33
	v_sqrt_f32_e32 v35, v35
	v_fma_f32 v32, v32, v138, v138
	v_rcp_f32_e32 v32, v32
	v_lshlrev_b32_e32 v36, 16, v178
	v_mul_f32_e32 v33, v35, v33
	v_mul_f32_e32 v178, v33, v36
	v_fmac_f32_e32 v178, v34, v177
	v_exp_f32_e32 v33, v56
	v_mul_f32_e32 v56, v34, v55
	v_exp_f32_e32 v32, v32
	v_exp_f32_e32 v34, v41
	v_add_f32_e32 v33, 1.0, v33
	v_rcp_f32_e32 v33, v33
	v_fma_f32 v35, -v32, v32, 1.0
	v_fma_f32 v34, v34, v138, v138
	v_sqrt_f32_e32 v35, v35
	v_rcp_f32_e32 v34, v34
	v_lshlrev_b32_e32 v36, 16, v179
	v_mul_f32_e32 v33, v35, v33
	v_mul_f32_e32 v179, v33, v36
	v_exp_f32_e32 v33, v57
	v_exp_f32_e32 v34, v34
	v_fmac_f32_e32 v179, v32, v178
	v_mul_f32_e32 v57, v32, v56
	v_exp_f32_e32 v32, v42
	v_add_f32_e32 v33, 1.0, v33
	v_fma_f32 v35, -v34, v34, 1.0
	v_rcp_f32_e32 v33, v33
	v_sqrt_f32_e32 v35, v35
	v_fma_f32 v32, v32, v138, v138
	v_rcp_f32_e32 v32, v32
	v_lshlrev_b32_e32 v36, 16, v180
	v_mul_f32_e32 v33, v35, v33
	v_mul_f32_e32 v180, v33, v36
	v_fmac_f32_e32 v180, v34, v179
	v_exp_f32_e32 v33, v58
	v_mul_f32_e32 v58, v34, v57
	v_exp_f32_e32 v32, v32
	v_exp_f32_e32 v34, v43
	v_add_f32_e32 v33, 1.0, v33
	v_rcp_f32_e32 v33, v33
	v_fma_f32 v35, -v32, v32, 1.0
	v_fma_f32 v34, v34, v138, v138
	v_sqrt_f32_e32 v35, v35
	v_rcp_f32_e32 v34, v34
	s_waitcnt lgkmcnt(13)
	v_lshlrev_b32_e32 v36, 16, v181
	v_mul_f32_e32 v33, v35, v33
	v_mul_f32_e32 v181, v33, v36
	v_exp_f32_e32 v33, v59
	v_exp_f32_e32 v34, v34
	v_fmac_f32_e32 v181, v32, v180
	v_mul_f32_e32 v59, v32, v58
	v_exp_f32_e32 v32, v44
	v_add_f32_e32 v33, 1.0, v33
	v_fma_f32 v35, -v34, v34, 1.0
	v_rcp_f32_e32 v33, v33
	v_sqrt_f32_e32 v35, v35
	v_fma_f32 v32, v32, v138, v138
	v_rcp_f32_e32 v32, v32
	s_waitcnt lgkmcnt(12)
	v_lshlrev_b32_e32 v36, 16, v182
	v_mul_f32_e32 v33, v35, v33
	v_mul_f32_e32 v182, v33, v36
	v_fmac_f32_e32 v182, v34, v181
	v_exp_f32_e32 v33, v60
	v_mul_f32_e32 v60, v34, v59
	v_exp_f32_e32 v32, v32
	v_exp_f32_e32 v34, v45
	v_add_f32_e32 v33, 1.0, v33
	v_rcp_f32_e32 v33, v33
	v_fma_f32 v35, -v32, v32, 1.0
	v_fma_f32 v34, v34, v138, v138
	v_sqrt_f32_e32 v35, v35
	v_rcp_f32_e32 v34, v34
	s_waitcnt lgkmcnt(11)
	v_lshlrev_b32_e32 v36, 16, v183
	v_mul_f32_e32 v33, v35, v33
	v_mul_f32_e32 v183, v33, v36
	v_exp_f32_e32 v33, v61
	v_exp_f32_e32 v34, v34
	v_fmac_f32_e32 v183, v32, v182
	v_mul_f32_e32 v61, v32, v60
	v_exp_f32_e32 v32, v46
	v_add_f32_e32 v33, 1.0, v33
	v_fma_f32 v35, -v34, v34, 1.0
	v_rcp_f32_e32 v33, v33
	v_sqrt_f32_e32 v35, v35
	v_fma_f32 v32, v32, v138, v138
	v_rcp_f32_e32 v32, v32
	s_waitcnt lgkmcnt(10)
	v_lshlrev_b32_e32 v36, 16, v184
	v_mul_f32_e32 v33, v35, v33
	v_mul_f32_e32 v184, v33, v36
	v_fmac_f32_e32 v184, v34, v183
	v_exp_f32_e32 v33, v62
	v_mul_f32_e32 v62, v34, v61
	v_exp_f32_e32 v34, v47
	v_exp_f32_e32 v32, v32
	v_add_f32_e32 v33, 1.0, v33
	v_rcp_f32_e32 v33, v33
	v_fma_f32 v34, v34, v138, v138
	v_fma_f32 v35, -v32, v32, 1.0
	v_rcp_f32_e32 v34, v34
	v_sqrt_f32_e32 v35, v35
	s_waitcnt lgkmcnt(9)
	v_lshlrev_b32_e32 v36, 16, v185
	v_mul_f32_e32 v186, v32, v62
	v_mul_f32_e32 v33, v35, v33
	v_exp_f32_e32 v35, v63
	v_exp_f32_e32 v34, v34
	v_mul_f32_e32 v63, v33, v36
	v_fmac_f32_e32 v63, v32, v184
	v_add_f32_e32 v33, 1.0, v35
	v_fma_f32 v35, -v34, v34, 1.0
	v_rcp_f32_e32 v33, v33
	v_sqrt_f32_e32 v35, v35
	s_waitcnt lgkmcnt(8)
	v_lshlrev_b32_e32 v32, 16, v187
	v_mul_f32_e32 v187, v34, v186
	v_mul_f32_e32 v33, v35, v33
	v_mul_f32_e32 v185, v33, v32
	v_and_b32_e32 v33, 64, v153
	v_xor_b32_e32 v32, 32, v153
	v_add_u32_e32 v33, 64, v33
	v_cmp_lt_i32_e64 s[18:19], v32, v33
	v_fmac_f32_e32 v185, v34, v63
	s_nop 0
	v_cndmask_b32_e64 v32, v153, v32, s[18:19]
	v_lshlrev_b32_e32 v157, 2, v32
	ds_bpermute_b32 v188, v157, v187
	ds_bpermute_b32 v189, v157, v185
	s_and_saveexec_b64 s[18:19], vcc
	s_cbranch_execz .LBB0_299
	s_waitcnt lgkmcnt(0)
	v_fma_f32 v32, v188, v185, v189
	v_mul_f32_e32 v33, v187, v188
	v_add_u32_e32 v35, s98, v147
	ds_write2_b32 v35, v33, v32 offset1:32

; #define LAS __attribute__((address_space(3)))
; #define LDS_BARRIER() do { asm volatile("s_waitcnt lgkmcnt(0)" ::: "memory"); __builtin_amdgcn_s_barrier(); asm volatile("" ::: "memory"); } while (0)
; template <int dir>
; __device__ __forceinline__ void lru_pass(LAS unsigned char* lds, const Params& P, int b, int h, int q, bool dry) {
;     ...
;     {
; #pragma unroll
;         for (int i = 0; i < 2; ++i) { const int idx = tid + i * NTHREADS, gate = idx >> 9, n = (idx >> 4) & 31, kc = idx & 15;
;             *(LAS u32x4*)(WB + (gate * 32 + n) * XC_PITCH + kc * 16) = *(const u32x4*)(LruW + ((size_t)((dir * 2 + gate) * 8 + h) * 128 + q * 32 + n) * 128 + kc * 8); }
;         const float br = -LOG2E * P.lru_ba[(dir * 8 + h) * 128 + chl], bi = -LOG2E * P.lru_bx[(dir * 8 + h) * 128 + chl];
;         const float lam = P.lru_lambda[dir * 1024 + ch];
;         const float cl = -8.0f * LOG2E * log1pf(__expf(-lam));
;         float carry = 0.f;
;         LruTile cur = lru_tile(Z, ZC, b, h, dir, 0);
;         u32x4 rows[11];
;         constexpr int NIN = dir == 0 ? 2 : 4;
;         u32x4 inr[NIN];
;         lru_load_rows(rows, cur, tr, cgp);
;     ...
;         LDS_BARRIER();
;         if (dir == 0) {
; #pragma unroll
;             for (int i = 0; i < 4; ++i) { const int id = tid + i * NTHREADS; *(u32x4*)(Hg + (size_t)(t0_prev + (id >> 3)) * DM + (id & 7) * 4) = *(const LAS u32x4*)(TOUT + (id >> 3) * IO_WP + (id & 7) * 16); }
.Lpp_f_noy:
	s_waitcnt lgkmcnt(0)
	s_barrier
	v_add_u32_e32 v0, v129, v149
	ds_read_b128 v[0:3], v0
	v_add_u32_e32 v4, s97, v148
	v_ashrrev_i32_e32 v5, 31, v4
	v_lshlrev_b64 v[4:5], 12, v[4:5]
	v_lshl_add_u64 v[8:9], v[130:131], 0, v[4:5]
	v_add_u32_e32 v4, v129, v146
	ds_read_b128 v[4:7], v4
	s_waitcnt lgkmcnt(1)
	global_store_dwordx4 v[8:9], v[0:3], off
	v_cmp_gt_i32_e32 vcc, 64, v128
	s_nop 0
	v_add_u32_e32 v0, s97, v145
	v_ashrrev_i32_e32 v1, 31, v0
	v_lshlrev_b64 v[0:1], 12, v[0:1]
	v_lshl_add_u64 v[0:1], v[130:131], 0, v[0:1]
	s_waitcnt lgkmcnt(0)
	global_store_dwordx4 v[0:1], v[4:7], off
	v_add_u32_e32 v0, v129, v144
	ds_read_b128 v[0:3], v0
	v_add_u32_e32 v4, s97, v143
	v_ashrrev_i32_e32 v5, 31, v4
	v_lshlrev_b64 v[4:5], 12, v[4:5]
	v_lshl_add_u64 v[8:9], v[130:131], 0, v[4:5]
	v_add_u32_e32 v4, v129, v142
	ds_read_b128 v[4:7], v4
	s_waitcnt lgkmcnt(1)
	global_store_dwordx4 v[8:9], v[0:3], off
	s_nop 1
	v_add_u32_e32 v0, s97, v141
	v_ashrrev_i32_e32 v1, 31, v0
	v_lshlrev_b64 v[0:1], 12, v[0:1]
	v_lshl_add_u64 v[0:1], v[130:131], 0, v[0:1]
	s_waitcnt lgkmcnt(0)
	global_store_dwordx4 v[0:1], v[4:7], off
	s_waitcnt vmcnt(0) lgkmcnt(0)
	s_barrier
	s_lshr_b32 s18, s2, 5
	s_lshl_b32 s18, s18, 3
	s_and_b32 s19, s2, 7
	s_or_b32 s18, s18, s19
	s_lshl_b32 s18, s18, 8
	s_add_u32 s18, s18, 0x84008
	s_add_u32 s18, s22, s18
	s_addc_u32 s19, s23, 0
	v_mov_b32_e32 v0, 0
	v_mov_b32_e32 v1, 1
	v_cmp_eq_u32_e32 vcc, 0, v167
	s_and_saveexec_b64 s[20:21], vcc
	global_atomic_add v0, v1, s[18:19]
	s_or_b64 exec, exec, s[20:21]
	s_add_u32 s42, s22, 0x1b00000
	s_addc_u32 s43, s23, 0
	v_mov_b32_e32 v32, v167
	s_or_b32 s0, s26, 16
	v_and_b32_e32 v15, 31, v32
	v_or_b32_e32 v17, s28, v15
	v_add_u32_e32 v13, 0x200, v32
	v_or_b32_e32 v8, s27, v17
	v_ashrrev_i32_e32 v11, 9, v32
	v_ashrrev_i32_e32 v14, 9, v13
	v_lshlrev_b32_e32 v8, 2, v8
	v_mov_b32_e32 v9, v65
	v_lshl_add_u32 v2, v11, 3, s0
	v_lshl_add_u32 v6, v14, 3, s0
	v_lshl_add_u64 v[8:9], s[64:65], 0, v[8:9]
	s_movk_i32 s0, 0x1000
	v_add_co_u32_e32 v8, vcc, s0, v8
	v_and_b32_e32 v12, 15, v32
	s_nop 0
	v_addc_co_u32_e32 v9, vcc, 0, v9, vcc
	global_load_dword v16, v[8:9], off
	v_bfe_u32 v10, v32, 4, 5
	v_lshlrev_b32_e32 v64, 4, v12
	v_ashrrev_i32_e32 v3, 31, v2
	v_ashrrev_i32_e32 v7, 31, v6
	v_or_b32_e32 v4, s28, v10
	v_lshl_add_u64 v[0:1], s[38:39], 0, v[64:65]
	v_lshlrev_b64 v[2:3], 15, v[2:3]
	v_lshlrev_b64 v[6:7], 15, v[6:7]
	v_lshlrev_b32_e32 v4, 8, v4
	v_mov_b32_e32 v5, v65
	v_lshl_add_u64 v[2:3], v[0:1], 0, v[2:3]
	v_lshl_add_u64 v[0:1], v[0:1], 0, v[6:7]
	v_lshl_add_u64 v[2:3], v[2:3], 0, v[4:5]
	v_lshl_add_u64 v[4:5], v[0:1], 0, v[4:5]
	global_load_dwordx4 v[0:3], v[2:3], off
	s_nop 0
	global_load_dwordx4 v[4:7], v[4:5], off
	v_lshrrev_b32_e32 v8, 1, v32
	v_lshlrev_b32_e32 v9, 2, v32
	v_and_b32_e32 v20, 12, v8
	v_lshl_or_b32 v11, v11, 5, v10
	v_add_u32_e32 v8, s88, v64
	v_lshl_or_b32 v14, v14, 5, v10
	v_mad_u64_u32 v[10:11], s[6:7], v11, s89, v[8:9]
	s_or_b32 s8, s26, 8
	v_and_or_b32 v20, v9, 16, v20
	v_lshlrev_b32_e32 v21, 2, v17
	v_mad_u64_u32 v[8:9], s[6:7], v14, s89, v[8:9]
	v_lshl_or_b32 v9, s8, 9, v21
	global_load_dword v14, v9, s[58:59]
	s_nop 0
	global_load_dword v9, v9, s[62:63]
	s_mov_b32 s80, 0x3f2aaaab
	s_mov_b32 s81, 0x3f317218
	s_mov_b32 s91, 0x7f800000
	s_mov_b32 s92, 0x33800000
	v_ashrrev_i32_e32 v33, 4, v32
	v_lshlrev_b32_e32 v34, 3, v12
	v_readfirstlane_b32 s4, v32
	s_lshl_b64 s[0:1], s[78:79], 11
	s_lshl_b32 s5, s8, 14
	s_ashr_i32 s6, s4, 6
	s_add_u32 s26, s0, s5
	s_addc_u32 s27, s1, 0
	s_lshl_b32 s0, s28, 1
	v_readlane_b32 s1, v255, 10
	v_and_b32_e32 v19, 3, v32
	s_add_u32 s0, s1, s0
	v_bfe_u32 v18, v32, 5, 1
	v_add_u32_e32 v44, 0, v64
	v_lshlrev_b32_e32 v64, 4, v19
	s_addc_u32 s1, s3, 0
	v_lshl_add_u64 v[136:137], s[0:1], 0, v[64:65]
	s_lshl_b32 s0, s6, 5
	v_lshlrev_b32_e32 v46, 4, v18
	v_or_b32_e32 v37, s0, v46
	v_add_u32_e32 v158, s86, v64
	v_or_b32_e32 v64, 4, v37
	s_movk_i32 s93, 0x880
	v_ashrrev_i32_e32 v36, 3, v32
	v_ashrrev_i32_e32 v38, 3, v13
	v_ashrrev_i32_e32 v140, 2, v32
	v_sub_u32_e32 v39, 0xff, v37
	v_sub_u32_e32 v64, 0xff, v64
	v_lshl_add_u32 v160, v33, 3, -1
	v_mul_lo_u32 v52, v33, s93
	v_lshl_or_b32 v110, v33, 13, v34
	v_mov_b32_e32 v111, v65
	v_lshlrev_b64 v[110:111], 1, v[110:111]
	v_lshl_add_u64 v[108:109], s[48:49], 0, v[110:111]
	global_load_dwordx4 v[68:71], v[108:109], off offset:-2048
	global_load_dwordx4 v[72:75], v[108:109], off
	global_load_dwordx4 v[76:79], v[108:109], off offset:2048
	v_lshl_add_u64 v[108:109], s[50:51], 0, v[110:111]
	global_load_dwordx4 v[80:83], v[108:109], off
	v_lshl_add_u64 v[108:109], s[56:57], 0, v[110:111]
	global_load_dwordx4 v[84:87], v[108:109], off
	v_lshl_add_u64 v[108:109], s[60:61], 0, v[110:111]
	global_load_dwordx4 v[88:91], v[108:109], off
	v_lshl_add_u64 v[108:109], s[66:67], 0, v[110:111]
	global_load_dwordx4 v[92:95], v[108:109], off
	v_lshl_add_u64 v[108:109], s[70:71], 0, v[110:111]
	global_load_dwordx4 v[96:99], v[108:109], off
	v_lshl_add_u64 v[108:109], s[72:73], 0, v[110:111]
	global_load_dwordx4 v[100:103], v[108:109], off
	v_lshl_add_u64 v[108:109], s[74:75], 0, v[110:111]
	global_load_dwordx4 v[104:107], v[108:109], off
	v_lshl_add_u64 v[108:109], s[76:77], 0, v[110:111]
	global_load_dwordx4 v[108:111], v[108:109], off
	s_waitcnt vmcnt(14)
	ds_write_b128 v10, v[0:3]
	s_waitcnt vmcnt(13)
; #define LAS __attribute__((address_space(3)))
; template <int dir>
; __device__ __forceinline__ void lru_pass(LAS unsigned char* lds, const Params& P, int b, int h, int q, bool dry) {
;     ...
;     {
; #pragma unroll
;         for (int i = 0; i < 2; ++i) { const int idx = tid + i * NTHREADS, gate = idx >> 9, n = (idx >> 4) & 31, kc = idx & 15;
;             *(LAS u32x4*)(WB + (gate * 32 + n) * XC_PITCH + kc * 16) = *(const u32x4*)(LruW + ((size_t)((dir * 2 + gate) * 8 + h) * 128 + q * 32 + n) * 128 + kc * 8); }
;         const float br = -LOG2E * P.lru_ba[(dir * 8 + h) * 128 + chl], bi = -LOG2E * P.lru_bx[(dir * 8 + h) * 128 + chl];
;         const float lam = P.lru_lambda[dir * 1024 + ch];
;         const float cl = -8.0f * LOG2E * log1pf(__expf(-lam));
;         float carry = 0.f;
;         LruTile cur = lru_tile(Z, ZC, b, h, dir, 0);
;         u32x4 rows[11];
;         constexpr int NIN = dir == 0 ? 2 : 4;
;         u32x4 inr[NIN];
;         lru_load_rows(rows, cur, tr, cgp);
	ds_write_b128 v8, v[4:7]
	v_mul_f32_e32 v11, 0xbfb8aa3b, v16
	v_exp_f32_e32 v11, v11
	v_mul_lo_u32 v57, v39, s89
	v_mul_lo_u32 v58, v39, s30
	v_mul_lo_u32 v114, v64, s89
	v_add_f32_e32 v2, 1.0, v11
	v_add_f32_e32 v3, -1.0, v2
	v_frexp_mant_f32_e32 v4, v2
	v_cvt_f64_f32_e32 v[0:1], v2
	v_sub_f32_e32 v5, v3, v2
	v_frexp_exp_i32_f64_e32 v0, v[0:1]
	v_cmp_gt_f32_e32 vcc, s80, v4
	v_sub_f32_e32 v3, v11, v3
	v_add_f32_e32 v1, 1.0, v5
	v_subbrev_co_u32_e32 v0, vcc, 0, v0, vcc
	v_add_f32_e32 v1, v3, v1
	v_sub_u32_e32 v3, 0, v0
	v_ldexp_f32 v2, v2, v3
	v_ldexp_f32 v1, v1, v3
	v_add_f32_e32 v3, -1.0, v2
	v_add_f32_e32 v4, 1.0, v2
	v_add_f32_e32 v5, 1.0, v3
	v_add_f32_e32 v6, -1.0, v4
	v_sub_f32_e32 v5, v2, v5
	v_sub_f32_e32 v2, v2, v6
	v_add_f32_e32 v5, v1, v5
	v_add_f32_e32 v1, v1, v2
	v_add_f32_e32 v7, v4, v1
	v_rcp_f32_e32 v8, v7
	v_add_f32_e32 v2, v3, v5
	v_sub_f32_e32 v4, v7, v4
	v_sub_f32_e32 v3, v2, v3
	v_sub_f32_e32 v1, v1, v4
	v_mul_f32_e32 v4, v2, v8
	v_sub_f32_e32 v3, v5, v3
	v_mul_f32_e32 v5, v7, v4
	v_fma_f32 v10, v4, v7, -v5
	v_fmac_f32_e32 v10, v4, v1
	v_add_f32_e32 v16, v5, v10
	v_sub_f32_e32 v21, v2, v16
	v_sub_f32_e32 v2, v2, v21
	v_sub_f32_e32 v5, v16, v5
	v_sub_f32_e32 v2, v2, v16
	v_sub_f32_e32 v5, v5, v10
	v_add_f32_e32 v2, v3, v2
	v_add_f32_e32 v2, v5, v2
	v_add_f32_e32 v3, v21, v2
	v_mul_f32_e32 v5, v8, v3
	v_sub_f32_e32 v10, v21, v3
	v_mul_f32_e32 v16, v7, v5
	v_add_f32_e32 v2, v2, v10
	v_add_f32_e32 v10, v4, v5
	v_fma_f32 v7, v5, v7, -v16
	v_sub_f32_e32 v4, v10, v4
	v_fmac_f32_e32 v7, v5, v1
	v_sub_f32_e32 v1, v5, v4
	v_add_f32_e32 v4, v16, v7
	v_sub_f32_e32 v5, v4, v16
	v_sub_f32_e32 v16, v3, v4
	v_sub_f32_e32 v3, v3, v16
	v_sub_f32_e32 v3, v3, v4
	v_cvt_f32_i32_e32 v0, v0
	v_sub_f32_e32 v5, v5, v7
	v_add_f32_e32 v2, v2, v3
	v_add_f32_e32 v2, v5, v2
	v_add_f32_e32 v2, v16, v2
	v_mul_f32_e32 v2, v8, v2
	v_mul_f32_e32 v6, 0x3f317218, v0
	v_add_f32_e32 v1, v1, v2
	v_add_f32_e32 v2, v10, v1
	v_fma_f32 v5, v0, s81, -v6
	v_fmac_f32_e32 v5, 0xb102e308, v0
	v_sub_f32_e32 v0, v2, v10
	v_mul_f32_e32 v3, v2, v2
	v_sub_f32_e32 v0, v1, v0
	v_add_f32_e32 v1, v6, v5
	v_fmamk_f32 v4, v3, 0x3e9b6dac, v200
	v_sub_f32_e32 v6, v1, v6
	v_fmaak_f32 v4, v3, v4, 0x3f2aaada
	v_sub_f32_e32 v5, v5, v6
	v_ldexp_f32 v6, v2, 1
	v_mul_f32_e32 v2, v2, v3
	v_mul_f32_e32 v2, v2, v4
	v_add_f32_e32 v3, v6, v2
	v_sub_f32_e32 v4, v3, v6
	v_ldexp_f32 v0, v0, 1
	v_sub_f32_e32 v2, v2, v4
	v_add_f32_e32 v0, v0, v2
	v_add_f32_e32 v2, v3, v0
	v_sub_f32_e32 v3, v2, v3
	v_sub_f32_e32 v0, v0, v3
	v_add_f32_e32 v3, v1, v2
	v_sub_f32_e32 v4, v3, v1
	v_sub_f32_e32 v6, v3, v4
	v_sub_f32_e32 v1, v1, v6
	v_sub_f32_e32 v2, v2, v4
	v_add_f32_e32 v1, v2, v1
	v_add_f32_e32 v2, v5, v0
	v_sub_f32_e32 v4, v2, v5
	v_add_f32_e32 v1, v2, v1
	v_sub_f32_e32 v6, v2, v4
	v_add_f32_e32 v2, v3, v1
	v_sub_f32_e32 v5, v5, v6
	v_sub_f32_e32 v0, v0, v4
	v_sub_f32_e32 v3, v2, v3
	v_add_f32_e32 v0, v0, v5
	v_sub_f32_e32 v1, v1, v3
	v_add_f32_e32 v0, v0, v1
	v_add_f32_e32 v0, v2, v0
	v_cmp_neq_f32_e32 vcc, s91, v11
	v_mov_b32_e32 v1, v65
	v_mul_lo_u32 v115, v64, s30
	v_cndmask_b32_e32 v0, v201, v0, vcc
	v_cmp_ngt_f32_e32 vcc, -1.0, v11
	v_mul_lo_u32 v206, v39, s87
	v_mul_lo_u32 v210, v64, s87
	v_cndmask_b32_e32 v0, v202, v0, vcc
	v_cmp_neq_f32_e32 vcc, -1.0, v11
	v_ashrrev_i32_e32 v39, 31, v38
	v_sub_u32_e32 v41, 0xfe, v37
	v_cndmask_b32_e32 v0, v203, v0, vcc
	v_cmp_lt_f32_e64 vcc, |v11|, s92
	v_mul_lo_u32 v59, v41, s89
	v_mul_lo_u32 v60, v41, s30
	v_cndmask_b32_e32 v6, v0, v11, vcc
	v_lshlrev_b32_e32 v2, 4, v32
	v_and_b32_e32 v2, 0x70, v2
	v_lshlrev_b32_e32 v1, 2, v15
	v_add_u32_e32 v45, s95, v2
	v_or3_b32 v2, v19, v20, s0
	s_and_b32 s0, s4, 0x3fffffc0
	v_add_u32_e32 v161, s94, v1
	s_cmp_eq_u32 s6, 7
	v_lshl_add_u32 v254, s0, 2, v161
	s_cselect_b64 s[0:1], -1, 0
	s_cmp_eq_u32 s6, 6
	s_cselect_b64 s[16:17], -1, 0
	s_cmp_eq_u32 s6, 5
	s_cselect_b64 s[4:5], -1, 0
	s_cmp_eq_u32 s6, 4
	s_cselect_b64 s[8:9], -1, 0
	s_cmp_eq_u32 s6, 3
	s_cselect_b64 s[10:11], -1, 0
	s_cmp_eq_u32 s6, 2
	s_cselect_b64 s[12:13], -1, 0
	s_cmp_eq_u32 s6, 1
	s_cselect_b64 s[14:15], -1, 0
	s_lshl_b32 s6, s25, 7
	s_and_b32 s6, s6, 0xe00
	s_lshl_b32 s7, s29, 7
	s_or_b32 s6, s7, s6
	s_add_u32 s6, s6, s44
	v_add_u32_e32 v50, s95, v1
	v_add_u32_e32 v1, 0x400, v32
	s_addc_u32 s7, 0, s45
	v_ashrrev_i32_e32 v40, 3, v1
	v_add_u32_e32 v1, 0x600, v32
	v_and_b32_e32 v32, 7, v32
	s_add_u32 s18, s84, s46
	v_lshlrev_b32_e32 v64, 4, v32
	v_lshl_or_b32 v32, v33, 10, v34
	v_mov_b32_e32 v33, v65
	s_addc_u32 s19, s85, s47
	v_lshl_add_u64 v[144:145], v[32:33], 1, s[18:19]
	v_lshlrev_b64 v[32:33], 12, v[38:39]
	v_lshl_add_u64 v[32:33], s[6:7], 0, v[32:33]
	v_mul_lo_u32 v207, v41, s87
	v_lshl_add_u64 v[32:33], v[32:33], 0, v[64:65]
	v_ashrrev_i32_e32 v41, 31, v40
	v_or_b32_e32 v43, 2, v37
	v_lshl_add_u64 v[252:253], s[42:43], 0, v[32:33]
	v_lshlrev_b64 v[32:33], 12, v[40:41]
	v_ashrrev_i32_e32 v42, 3, v1
	v_sub_u32_e32 v43, 0xff, v43
	v_or_b32_e32 v63, 3, v37
	v_or_b32_e32 v66, 5, v37
	v_or_b32_e32 v67, 6, v37
	v_or_b32_e32 v120, 7, v37
	v_or_b32_e32 v123, 8, v37
	v_or_b32_e32 v126, 9, v37
	v_or_b32_e32 v129, 10, v37
	v_or_b32_e32 v132, 11, v37
	v_or_b32_e32 v135, 12, v37
	v_or_b32_e32 v142, 13, v37
	v_or_b32_e32 v143, 14, v37
	v_or_b32_e32 v37, 15, v37
	v_lshl_add_u64 v[32:33], s[6:7], 0, v[32:33]
	v_mul_lo_u32 v61, v43, s89
	v_mul_lo_u32 v62, v43, s30
	v_sub_u32_e32 v37, 0xff, v37
	v_mul_lo_u32 v208, v43, s87
	v_lshl_add_u64 v[32:33], v[32:33], 0, v[64:65]
	v_ashrrev_i32_e32 v43, 31, v42
	v_sub_u32_e32 v2, 0xff, v2
	v_mul_lo_u32 v204, v37, s89
	v_mul_lo_u32 v205, v37, s30
	v_mul_lo_u32 v221, v37, s87
	v_ashrrev_i32_e32 v37, 31, v36
	v_lshl_add_u64 v[154:155], s[42:43], 0, v[32:33]
	v_lshlrev_b64 v[32:33], 12, v[42:43]
	v_mul_lo_u32 v2, v2, s89
	v_mul_lo_u32 v53, v36, s30
	v_sub_u32_e32 v63, 0xff, v63
	v_sub_u32_e32 v66, 0xff, v66
	v_sub_u32_e32 v67, 0xff, v67
	v_sub_u32_e32 v120, 0xff, v120
	v_sub_u32_e32 v123, 0xff, v123
	v_sub_u32_e32 v126, 0xff, v126
	v_lshlrev_b64 v[36:37], 12, v[36:37]
	v_lshl_add_u64 v[32:33], s[6:7], 0, v[32:33]
	v_lshlrev_b32_e32 v35, 5, v12
	v_add_u32_e32 v47, 0, v2
	v_mov_b32_e32 v2, s88
	v_lshl_add_u32 v49, v17, 1, 0
	v_lshl_add_u32 v51, v15, 1, s86
	v_mul_lo_u32 v112, v63, s89
	v_mul_lo_u32 v113, v63, s30
	v_mul_lo_u32 v116, v66, s89
	v_mul_lo_u32 v117, v66, s30
	v_mul_lo_u32 v118, v67, s89
	v_mul_lo_u32 v119, v67, s30
	v_mul_lo_u32 v121, v120, s89
	v_mul_lo_u32 v122, v120, s30
	v_mul_lo_u32 v124, v123, s89
	v_mul_lo_u32 v125, v123, s30
	v_mul_lo_u32 v127, v126, s89
	v_mul_lo_u32 v128, v126, s30
	v_sub_u32_e32 v129, 0xff, v129
	v_sub_u32_e32 v132, 0xff, v132
	v_sub_u32_e32 v135, 0xff, v135
	v_sub_u32_e32 v142, 0xff, v142
	v_sub_u32_e32 v143, 0xff, v143
	v_mul_lo_u32 v211, v66, s87
	v_mul_lo_u32 v212, v67, s87
	v_mul_lo_u32 v120, v120, s87
	v_mul_lo_u32 v123, v123, s87
	v_mul_lo_u32 v126, v126, s87
	v_lshl_add_u64 v[36:37], s[6:7], 0, v[36:37]
	v_lshl_add_u64 v[32:33], v[32:33], 0, v[64:65]
	v_mov_b32_e32 v66, v65
	v_mov_b32_e32 v67, v65
	s_waitcnt vmcnt(12)
; template <int dir>
; __device__ __forceinline__ void lru_pass(LAS unsigned char* lds, const Params& P, int b, int h, int q, bool dry) {
;     ...
;         const float br = -LOG2E * P.lru_ba[(dir * 8 + h) * 128 + chl], bi = -LOG2E * P.lru_bx[(dir * 8 + h) * 128 + chl];
;         const float lam = P.lru_lambda[dir * 1024 + ch];
;         const float cl = -8.0f * LOG2E * log1pf(__expf(-lam));
;         float carry = 0.f;
;         LruTile cur = lru_tile(Z, ZC, b, h, dir, 0);
;         u32x4 rows[11];
;         constexpr int NIN = dir == 0 ? 2 : 4;
;         u32x4 inr[NIN];
;         lru_load_rows(rows, cur, tr, cgp);
; #pragma unroll
;         for (int i = 0; i < NIN; ++i) inr[i] = (u32x4){0u, 0u, 0u, 0u};
;         int t0_prev = 0;
;     ...
;             f32x16 zr, zi;
; #pragma unroll
;             for (int v = 0; v < 16; ++v) { zr[v] = br; zi[v] = bi; }
;             const int sbase = 32 * wid + 16 * g;
	v_mul_f32_e32 v0, 0xbfb8aa3b, v14
	s_waitcnt vmcnt(11)
	v_mul_f32_e32 v16, 0xbfb8aa3b, v9
	v_mad_u32_u24 v48, v15, s89, v2
	v_mul_lo_u32 v54, v38, s30
	v_mul_lo_u32 v55, v40, s30
	v_mul_lo_u32 v56, v42, s30
	v_ashrrev_i32_e32 v138, 2, v13
	v_mul_lo_u32 v130, v129, s89
	v_mul_lo_u32 v131, v129, s30
	v_mul_lo_u32 v133, v132, s89
	v_mul_lo_u32 v134, v132, s30
	v_mul_lo_u32 v146, v135, s89
	v_mul_lo_u32 v147, v135, s30
	v_mul_lo_u32 v148, v142, s89
	v_mul_lo_u32 v149, v142, s30
	v_mul_lo_u32 v162, v143, s89
	v_mul_lo_u32 v163, v143, s30
	v_mul_lo_u32 v63, v63, s87
	v_mul_lo_u32 v129, v129, s87
	v_mul_lo_u32 v132, v132, s87
	v_mul_lo_u32 v135, v135, s87
	v_mul_lo_u32 v219, v142, s87
	v_mul_lo_u32 v220, v143, s87
	v_lshl_add_u64 v[36:37], v[36:37], 0, v[64:65]
	v_lshl_add_u64 v[150:151], s[42:43], 0, v[32:33]
	v_mov_b32_e32 v64, v65
	v_add_u32_e32 v32, 0, v35
	v_add_u32_e32 v180, v49, v112
	v_add_u32_e32 v181, v50, v113
	v_add_u32_e32 v182, v49, v114
	v_add_u32_e32 v183, v50, v115
	v_add_u32_e32 v184, v49, v116
	v_add_u32_e32 v185, v50, v117
	v_add_u32_e32 v186, v49, v118
	v_add_u32_e32 v187, v50, v119
	v_add_u32_e32 v188, v49, v121
	v_add_u32_e32 v189, v50, v122
	v_add_u32_e32 v190, v49, v124
	v_add_u32_e32 v191, v50, v125
	v_add_u32_e32 v192, v49, v127
	v_add_u32_e32 v213, v51, v120
	v_add_u32_e32 v214, v51, v123
	v_add_u32_e32 v215, v51, v126
	v_mov_b64_e32 v[114:115], v[66:67]
	v_mov_b64_e32 v[118:119], v[66:67]
	v_mov_b64_e32 v[122:123], v[66:67]
	v_mov_b64_e32 v[126:127], v[66:67]
	s_mov_b32 s78, 0
	v_mov_b32_e32 v156, 0xff800000
	v_mul_f32_e32 v159, 0xc138aa3b, v6
	v_rcp_f32_e32 v159, v159
	s_nop 0
	v_cmp_eq_u32_e32 vcc, 0, v18
	v_mul_lo_u32 v164, v140, s87
	v_ashrrev_i32_e32 v141, 31, v140
	v_mul_lo_u32 v152, v138, s87
	v_ashrrev_i32_e32 v139, 31, v138
	v_mov_b32_e32 v1, v0
	v_mov_b32_e32 v2, v0
	v_mov_b32_e32 v3, v0
	v_mov_b32_e32 v4, v0
	v_mov_b32_e32 v5, v0
	v_mov_b32_e32 v6, v0
	v_mov_b32_e32 v7, v0
	v_mov_b32_e32 v8, v0
	v_mov_b32_e32 v9, v0
	v_mov_b32_e32 v10, v0
	v_mov_b32_e32 v11, v0
	v_mov_b32_e32 v12, v0
	v_mov_b32_e32 v13, v0
	v_mov_b32_e32 v14, v0
	v_mov_b32_e32 v15, v0
	v_mov_b32_e32 v17, v16
	v_mov_b32_e32 v18, v16
	v_mov_b32_e32 v19, v16
	v_mov_b32_e32 v20, v16
	v_mov_b32_e32 v21, v16
	v_mov_b32_e32 v22, v16
	v_mov_b32_e32 v23, v16
	v_mov_b32_e32 v24, v16
	v_mov_b32_e32 v25, v16
	v_mov_b32_e32 v26, v16
	v_mov_b32_e32 v27, v16
	v_mov_b32_e32 v28, v16
	v_mov_b32_e32 v29, v16
	v_mov_b32_e32 v30, v16
	v_mov_b32_e32 v31, v16
	v_lshl_add_u64 v[142:143], s[42:43], 0, v[36:37]
	s_movk_i32 s28, 0x100
	v_mov_b32_e32 v222, 0
	s_mov_b64 s[44:45], 0
	s_movk_i32 s25, 0x700
	v_add_u32_e32 v165, 0x15c00, v32
	v_add_u32_e32 v166, v44, v52
	v_add_u32_e32 v168, v45, v53
	v_add_u32_e32 v169, v45, v54
	v_add_u32_e32 v170, v45, v55
	v_add_u32_e32 v171, v45, v56
	v_add_u32_e32 v172, v47, v46
	v_add_u32_e32 v173, v48, v46
	v_add_u32_e32 v174, v49, v57
	v_add_u32_e32 v175, v50, v58
	v_add_u32_e32 v176, v49, v59
	v_add_u32_e32 v177, v50, v60
	v_add_u32_e32 v178, v49, v61
	v_add_u32_e32 v179, v50, v62
	v_add_u32_e32 v193, v50, v128
	v_add_u32_e32 v194, v49, v130
	v_add_u32_e32 v195, v50, v131
	v_add_u32_e32 v196, v49, v133
	v_add_u32_e32 v197, v50, v134
	v_add_u32_e32 v198, v49, v146
	v_add_u32_e32 v199, v50, v147
	v_add_u32_e32 v200, v49, v148
	v_add_u32_e32 v201, v50, v149
	v_add_u32_e32 v202, v49, v162
	v_add_u32_e32 v203, v50, v163
	v_add_u32_e32 v204, v49, v204
	v_add_u32_e32 v205, v50, v205
	v_add_u32_e32 v206, v51, v206
	v_add_u32_e32 v207, v51, v207
	v_add_u32_e32 v208, v51, v208
	v_add_u32_e32 v209, v51, v63
	v_add_u32_e32 v210, v51, v210
	v_add_u32_e32 v211, v51, v211
	v_add_u32_e32 v212, v51, v212
	v_add_u32_e32 v216, v51, v129
	v_add_u32_e32 v217, v51, v132
	v_add_u32_e32 v218, v51, v135
	v_add_u32_e32 v219, v51, v219
	v_add_u32_e32 v220, v51, v220
	v_add_u32_e32 v221, v51, v221
	v_mov_b64_e32 v[112:113], v[64:65]
	v_mov_b64_e32 v[116:117], v[64:65]
; template <int dir>
; __device__ __forceinline__ void lru_pass(LAS unsigned char* lds, const Params& P, int b, int h, int q, bool dry) {
;     ...
;         int t0_prev = 0;
;         for (int sc = 0; sc < 9; ++sc) {
;             const bool isctx = (sc == 0);
;             const int t0 = cur.t0;
; #pragma unroll
;             for (int j = 0; j < 11; ++j) { if (j != 0 && j < 9) continue;
;                 const int t = t0 + tr * 8 - 1 + j; if (t < 0 || t >= cur.L) rows[j] = (u32x4){0u, 0u, 0u, 0u}; }
	v_mov_b64_e32 v[120:121], v[64:65]
	v_mov_b64_e32 v[124:125], v[64:65]
	s_mov_b32 s46, 0
	s_mov_b32 s29, 0
	v_lshrrev_b32_e32 v32, 8, v167
	v_mul_u32_u24_e32 v33, 0x3600, v32
	v_add_u32_e32 v168, v168, v33
	v_add_u32_e32 v169, v169, v33
	v_add_u32_e32 v170, v170, v33
	v_add_u32_e32 v171, v171, v33
	v_add_u32_e32 v169, 0xffffee00, v169
	v_add_u32_e32 v170, 0xffffdc00, v170
	v_add_u32_e32 v171, 0xffffca00, v171
	v_mul_u32_u24_e32 v66, 0x60000, v32
	v_mov_b32_e32 v67, 0
	v_lshl_add_u64 v[142:143], v[66:67], 0, v[142:143]
	v_lshl_add_u64 v[252:253], v[66:67], 0, v[252:253]
	v_lshl_add_u64 v[154:155], v[66:67], 0, v[154:155]
	v_lshl_add_u64 v[150:151], v[66:67], 0, v[150:151]
	s_mov_b32 s19, -1
	s_mov_b32 s18, 0xfffe0000
	v_lshl_add_u64 v[252:253], v[252:253], 0, s[18:19]
	s_mov_b32 s18, 0xfffc0000
	v_lshl_add_u64 v[154:155], v[154:155], 0, s[18:19]
	s_mov_b32 s18, 0xfffa0000
	v_lshl_add_u64 v[150:151], v[150:151], 0, s[18:19]
	v_mul_u32_u24_e32 v33, 0x1400, v32
	v_add_u32_e32 v164, v164, v33
	v_add_u32_e32 v152, v152, v33
	v_add_u32_e32 v152, 0xffffec00, v152
	v_lshlrev_b32_e32 v33, 6, v32
	v_add_u32_e32 v140, v140, v33
	v_add_u32_e32 v138, v138, v33
	v_add_u32_e32 v138, 0xffffffc0, v138
	v_lshrrev_b32_e32 v33, 6, v167
	s_nop 1
	v_readfirstlane_b32 s18, v33
	s_lshl_b32 s19, s18, 6
	s_sub_i32 s19, s19, 0xe0
	s_mul_i32 s20, s19, 0x110
	v_add_u32_e32 v172, s20, v172
	v_add_u32_e32 v174, s20, v174
	v_add_u32_e32 v176, s20, v176
	v_add_u32_e32 v178, s20, v178
	v_add_u32_e32 v180, s20, v180
	v_add_u32_e32 v182, s20, v182
	v_add_u32_e32 v184, s20, v184
	v_add_u32_e32 v186, s20, v186
	v_add_u32_e32 v188, s20, v188
	v_add_u32_e32 v190, s20, v190
	v_add_u32_e32 v192, s20, v192
	v_add_u32_e32 v194, s20, v194
	v_add_u32_e32 v196, s20, v196
	v_add_u32_e32 v198, s20, v198
	v_add_u32_e32 v200, s20, v200
	v_add_u32_e32 v202, s20, v202
	v_add_u32_e32 v204, s20, v204
	s_mul_i32 s20, s19, 0x90
	v_add_u32_e32 v175, s20, v175
	v_add_u32_e32 v177, s20, v177
	v_add_u32_e32 v179, s20, v179
	v_add_u32_e32 v181, s20, v181
	v_add_u32_e32 v183, s20, v183
	v_add_u32_e32 v185, s20, v185
	v_add_u32_e32 v187, s20, v187
	v_add_u32_e32 v189, s20, v189
	v_add_u32_e32 v191, s20, v191
	v_add_u32_e32 v193, s20, v193
	v_add_u32_e32 v195, s20, v195
	v_add_u32_e32 v197, s20, v197
	v_add_u32_e32 v199, s20, v199
	v_add_u32_e32 v201, s20, v201
	v_add_u32_e32 v203, s20, v203
	v_add_u32_e32 v205, s20, v205
	s_mul_i32 s20, s19, 0x50
	v_add_u32_e32 v206, s20, v206
	v_add_u32_e32 v207, s20, v207
	v_add_u32_e32 v208, s20, v208
	v_add_u32_e32 v209, s20, v209
	v_add_u32_e32 v210, s20, v210
	v_add_u32_e32 v211, s20, v211
	v_add_u32_e32 v212, s20, v212
	v_add_u32_e32 v213, s20, v213
	v_add_u32_e32 v214, s20, v214
	v_add_u32_e32 v215, s20, v215
	v_add_u32_e32 v216, s20, v216
	v_add_u32_e32 v217, s20, v217
	v_add_u32_e32 v218, s20, v218
	v_add_u32_e32 v219, s20, v219
	v_add_u32_e32 v220, s20, v220
	v_add_u32_e32 v221, s20, v221
	s_lshl_b32 s20, s18, 1
	s_sub_i32 s20, 7, s20
	s_lshl_b32 s20, s20, 8
	v_add_u32_e32 v254, s20, v254
	s_sub_i32 s18, 7, s18
	s_lshr_b32 s101, s18, 2
	s_or_b32 s19, s18, 4
	s_cmp_eq_u32 s19, 7
	s_cselect_b64 s[0:1], -1, 0
	s_cmp_eq_u32 s19, 6
	s_cselect_b64 s[16:17], -1, 0
	s_cmp_eq_u32 s19, 5
	s_cselect_b64 s[4:5], -1, 0
	s_cmp_eq_u32 s19, 4
	s_cselect_b64 s[8:9], -1, 0
	s_cmp_eq_u32 s19, 3
	s_cselect_b64 s[10:11], -1, 0
	s_cmp_eq_u32 s19, 2
	s_cselect_b64 s[12:13], -1, 0
	s_cmp_eq_u32 s19, 1
	s_cselect_b64 s[14:15], -1, 0
	s_mov_b32 s98, 0
	s_cmp_eq_u32 s101, 0
	s_cselect_b32 s99, 0x14400, 0
	s_cselect_b32 s100, 0, 0x400
	v_add_u32_e32 v33, 0x14000, v254
	v_mov_b32_e32 v66, 1.0
	v_mov_b32_e32 v67, 0
	ds_write2_b32 v33, v66, v67 offset1:32
	s_mov_b32 s40, 0x8000000
	s_mov_b32 s41, 0
	s_lshr_b32 s18, s2, 5
	s_lshl_b32 s18, s18, 3
	s_and_b32 s19, s2, 7
	s_or_b32 s18, s18, s19
	s_lshl_b32 s18, s18, 8
	s_add_u32 s18, s18, 0x84008
	s_add_u32 s18, s22, s18
	s_addc_u32 s19, s23, 0
	v_mov_b32_e32 v32, 0
	s_mov_b32 s21, 0x100000

; #define LAS __attribute__((address_space(3)))
; template <int dir>
; __device__ __forceinline__ void lru_pass(LAS unsigned char* lds, const Params& P, int b, int h, int q, bool dry) {
;     ...
;             { const int sl = 32 * wid + s_i; const int tlA = dir == 0 ? sl : 255 - sl;
;               const LAS unsigned char* ap = XC + tlA * XC_PITCH + 16 * g;
;               const LAS unsigned char* wrp = WB + nl * XC_PITCH + 16 * g; const LAS unsigned char* wip = wrp + 32 * XC_PITCH;
; #pragma unroll
;               for (int ks = 0; ks < 8; ++ks) { const bf16x8 A = *(const LAS bf16x8*)(ap + 32 * ks);
;                   const bf16x8 Br = *(const LAS bf16x8*)(wrp + 32 * ks), Bi = *(const LAS bf16x8*)(wip + 32 * ks);
;                   zr = __builtin_amdgcn_mfma_f32_32x32x16_bf16(A, Br, zr, 0, 0, 0); zi = __builtin_amdgcn_mfma_f32_32x32x16_bf16(A, Bi, zi, 0, 0, 0); } }
;             unsigned xcb[16], pk[16];
; #pragma unroll
;             for (int v = 0; v < 16; ++v) { const int s = sbase + v; const int tl = dir == 0 ? s : 255 - s; xcb[v] = *(const LAS bf16_t*)(XC + tl * XC_PITCH + chl * 2);
;                 if (dir == 0) pk[v] = *(const LAS bf16_t*)(TIN + tl * IO_NP + nl * 2); else pk[v] = *(const LAS unsigned*)(TIN + tl * IO_WP + nl * 4); }
;             float Pp = 1.f, E = 0.f;
; #pragma unroll
;             for (int v = 0; v < 16; ++v) {
;                 const float xcv = __uint_as_float(xcb[v] << 16);
;                 const float r = __builtin_amdgcn_rcpf(1.0f + __builtin_amdgcn_exp2f(zr[v]));
;                 const float ig = __builtin_amdgcn_rcpf(1.0f + __builtin_amdgcn_exp2f(zi[v]));
;                 const float a = __builtin_amdgcn_exp2f(cl * r);
;                 const float sq = __builtin_amdgcn_sqrtf(fmaf(-a, a, 1.0f));
;                 const float u = sq * ig * xcv;
;                 E = fmaf(a, E, u); Pp *= a; zr[v] = E; zi[v] = Pp; }
.LBB0_311:
	ds_read_b128 v[128:131], v172
	ds_read_b128 v[48:51], v173
	ds_read_b128 v[132:135], v172 offset:32
	ds_read_b128 v[52:55], v173 offset:32
	ds_read_b128 v[224:227], v172 offset:64
	ds_read_b128 v[56:59], v173 offset:64
	ds_read_b128 v[228:231], v172 offset:96
	ds_read_b128 v[60:63], v173 offset:96
	ds_read_b128 v[232:235], v172 offset:128
	ds_read_b128 v[236:239], v172 offset:160
	ds_read_b128 v[240:243], v172 offset:192
	ds_read_b128 v[244:247], v172 offset:224
	ds_read_b128 v[248:251], v173 offset:8704
	ds_read_b128 v[146:149], v173 offset:8736
	s_waitcnt lgkmcnt(12)
	v_mfma_f32_32x32x16_bf16 v[32:47], v[128:131], v[48:51], v[0:15]
	ds_read_b128 v[48:51], v173 offset:128
	s_waitcnt lgkmcnt(11)
	v_mfma_f32_32x32x16_bf16 v[32:47], v[132:135], v[52:55], v[32:47]
	ds_read_b128 v[52:55], v173 offset:160
	s_waitcnt lgkmcnt(10)
	v_mfma_f32_32x32x16_bf16 v[32:47], v[224:227], v[56:59], v[32:47]
	ds_read_b128 v[56:59], v173 offset:192
	s_waitcnt lgkmcnt(9)
	v_mfma_f32_32x32x16_bf16 v[32:47], v[228:231], v[60:63], v[32:47]
	ds_read_b128 v[60:63], v173 offset:224
	s_waitcnt lgkmcnt(3)
	v_mfma_f32_32x32x16_bf16 v[32:47], v[232:235], v[48:51], v[32:47]
	s_waitcnt lgkmcnt(2)
	v_mfma_f32_32x32x16_bf16 v[32:47], v[236:239], v[52:55], v[32:47]
	s_waitcnt lgkmcnt(1)
	v_mfma_f32_32x32x16_bf16 v[32:47], v[240:243], v[56:59], v[32:47]
	s_waitcnt lgkmcnt(0)
	v_mfma_f32_32x32x16_bf16 v[32:47], v[244:247], v[60:63], v[32:47]
	v_mfma_f32_32x32x16_bf16 v[48:63], v[128:131], v[248:251], v[16:31]
	ds_read_b128 v[128:131], v173 offset:8768
	s_nop 9
	v_exp_f32_e32 v32, v32
	v_exp_f32_e32 v33, v33
	v_exp_f32_e32 v34, v34
	v_exp_f32_e32 v35, v35
	v_exp_f32_e32 v36, v36
	v_exp_f32_e32 v37, v37
	v_exp_f32_e32 v38, v38
	v_exp_f32_e32 v39, v39
	v_exp_f32_e32 v40, v40
	v_exp_f32_e32 v41, v41
	v_mfma_f32_32x32x16_bf16 v[48:63], v[132:135], v[146:149], v[48:63]
	ds_read_b128 v[132:135], v173 offset:8800
	v_exp_f32_e32 v42, v42
	v_exp_f32_e32 v43, v43
	v_exp_f32_e32 v44, v44
	v_exp_f32_e32 v45, v45
	v_exp_f32_e32 v46, v46
	v_exp_f32_e32 v47, v47
	v_fma_f32 v32, v32, v159, v159
	v_fma_f32 v33, v33, v159, v159
	v_fma_f32 v34, v34, v159, v159
	v_fma_f32 v35, v35, v159, v159
	v_fma_f32 v36, v36, v159, v159
	s_waitcnt lgkmcnt(1)
	v_mfma_f32_32x32x16_bf16 v[48:63], v[224:227], v[128:131], v[48:63]
	ds_read_b128 v[224:227], v173 offset:8832
	v_fma_f32 v37, v37, v159, v159
	v_fma_f32 v38, v38, v159, v159
	v_fma_f32 v39, v39, v159, v159
	v_fma_f32 v40, v40, v159, v159
	v_fma_f32 v41, v41, v159, v159
	v_fma_f32 v42, v42, v159, v159
	v_fma_f32 v43, v43, v159, v159
	v_fma_f32 v44, v44, v159, v159
	v_fma_f32 v45, v45, v159, v159
	v_fma_f32 v46, v46, v159, v159
	v_fma_f32 v47, v47, v159, v159
	s_waitcnt lgkmcnt(1)
	v_mfma_f32_32x32x16_bf16 v[48:63], v[228:231], v[132:135], v[48:63]
	ds_read_b128 v[228:231], v173 offset:8864
	v_rcp_f32_e32 v32, v32
	v_rcp_f32_e32 v33, v33
	v_rcp_f32_e32 v34, v34
	v_rcp_f32_e32 v35, v35
	v_rcp_f32_e32 v36, v36
	v_rcp_f32_e32 v37, v37
	v_rcp_f32_e32 v38, v38
	v_rcp_f32_e32 v39, v39
	v_rcp_f32_e32 v40, v40
	v_rcp_f32_e32 v41, v41
	v_rcp_f32_e32 v42, v42
	s_waitcnt lgkmcnt(1)
	v_mfma_f32_32x32x16_bf16 v[48:63], v[232:235], v[224:227], v[48:63]
	ds_read_b128 v[128:131], v173 offset:8896
	v_rcp_f32_e32 v43, v43
	v_rcp_f32_e32 v44, v44
	v_rcp_f32_e32 v45, v45
	v_rcp_f32_e32 v46, v46
	v_rcp_f32_e32 v47, v47
	s_waitcnt lgkmcnt(1)
	v_mfma_f32_32x32x16_bf16 v[48:63], v[236:239], v[228:231], v[48:63]
	ds_read_b128 v[132:135], v173 offset:8928
	v_exp_f32_e32 v32, v32
	s_waitcnt lgkmcnt(1)
	v_mfma_f32_32x32x16_bf16 v[48:63], v[240:243], v[128:131], v[48:63]
	v_exp_f32_e32 v33, v33
	v_exp_f32_e32 v34, v34
	v_exp_f32_e32 v35, v35
	v_exp_f32_e32 v36, v36
	v_exp_f32_e32 v37, v37
	v_exp_f32_e32 v38, v38
	v_exp_f32_e32 v39, v39
	v_exp_f32_e32 v40, v40
	v_exp_f32_e32 v41, v41
	v_exp_f32_e32 v42, v42
	v_exp_f32_e32 v43, v43
	s_waitcnt lgkmcnt(0)
	v_mfma_f32_32x32x16_bf16 v[48:63], v[244:247], v[132:135], v[48:63]
	v_exp_f32_e32 v44, v44
	v_exp_f32_e32 v45, v45
	v_exp_f32_e32 v46, v46
	v_exp_f32_e32 v47, v47
	ds_read_u16 v162, v174
	ds_read_b32 v226, v175
	ds_read_u16 v163, v176
	ds_read_b32 v225, v177
	ds_read_u16 v232, v178
	ds_read_b32 v224, v179
	ds_read_u16 v233, v180
	ds_read_b32 v223, v181
	ds_read_u16 v234, v182
	ds_read_b32 v135, v183
	ds_read_u16 v235, v184
	ds_read_b32 v134, v185
	ds_read_u16 v236, v186
	ds_read_b32 v133, v187
	ds_read_u16 v237, v188
	ds_read_b32 v131, v189
	ds_read_u16 v146, v190
	ds_read_b32 v132, v191
	ds_read_u16 v147, v192
	ds_read_b32 v130, v193
	ds_read_u16 v148, v194
	ds_read_b32 v129, v195
	ds_read_u16 v149, v196
	ds_read_b32 v128, v197
	ds_read_u16 v239, v198
	ds_read_b32 v67, v199
	ds_read_u16 v240, v200
	ds_read_b32 v66, v201
	ds_read_u16 v241, v202
	ds_read_b32 v64, v203
	ds_read_u16 v242, v204
	ds_read_b32 v251, v205
	v_exp_f32_e32 v48, v48
	v_exp_f32_e32 v49, v49
	v_exp_f32_e32 v50, v50
	v_exp_f32_e32 v51, v51
	v_exp_f32_e32 v52, v52
	v_exp_f32_e32 v53, v53
	v_exp_f32_e32 v54, v54
	v_exp_f32_e32 v55, v55
	v_exp_f32_e32 v56, v56
	v_exp_f32_e32 v57, v57
	v_exp_f32_e32 v58, v58
	v_exp_f32_e32 v59, v59
	v_exp_f32_e32 v60, v60
	v_exp_f32_e32 v61, v61
	v_exp_f32_e32 v62, v62
	v_exp_f32_e32 v63, v63
	v_add_f32_e32 v48, 1.0, v48
	v_add_f32_e32 v49, 1.0, v49
	v_add_f32_e32 v50, 1.0, v50
	v_add_f32_e32 v51, 1.0, v51
	v_add_f32_e32 v52, 1.0, v52
	v_add_f32_e32 v53, 1.0, v53
	v_add_f32_e32 v54, 1.0, v54
	v_add_f32_e32 v55, 1.0, v55
	v_add_f32_e32 v56, 1.0, v56
	v_add_f32_e32 v57, 1.0, v57
	v_add_f32_e32 v58, 1.0, v58
	v_add_f32_e32 v59, 1.0, v59
	v_add_f32_e32 v60, 1.0, v60
	v_add_f32_e32 v61, 1.0, v61
	v_add_f32_e32 v62, 1.0, v62
	v_add_f32_e32 v63, 1.0, v63
	v_rcp_f32_e32 v48, v48
	v_rcp_f32_e32 v49, v49
	v_rcp_f32_e32 v50, v50
	v_rcp_f32_e32 v51, v51
	v_rcp_f32_e32 v52, v52
	v_rcp_f32_e32 v53, v53
	v_rcp_f32_e32 v54, v54
	v_rcp_f32_e32 v55, v55
	v_rcp_f32_e32 v56, v56
	v_rcp_f32_e32 v57, v57
	v_rcp_f32_e32 v58, v58
	v_rcp_f32_e32 v59, v59
	v_rcp_f32_e32 v60, v60
	v_rcp_f32_e32 v61, v61
	v_rcp_f32_e32 v62, v62
	v_rcp_f32_e32 v63, v63
	s_waitcnt lgkmcnt(0)
; template <int dir>
; __device__ __forceinline__ void lru_pass(LAS unsigned char* lds, const Params& P, int b, int h, int q, bool dry) {
;     ...
;             float Pp = 1.f, E = 0.f;
; #pragma unroll
;             for (int v = 0; v < 16; ++v) {
;                 const float xcv = __uint_as_float(xcb[v] << 16);
;                 const float r = __builtin_amdgcn_rcpf(1.0f + __builtin_amdgcn_exp2f(zr[v]));
;                 const float ig = __builtin_amdgcn_rcpf(1.0f + __builtin_amdgcn_exp2f(zi[v]));
;                 const float a = __builtin_amdgcn_exp2f(cl * r);
;                 const float sq = __builtin_amdgcn_sqrtf(fmaf(-a, a, 1.0f));
;                 const float u = sq * ig * xcv;
;                 E = fmaf(a, E, u); Pp *= a; zr[v] = E; zi[v] = Pp; }
;             const float Po = __shfl_xor(Pp, 32), Eo = __shfl_xor(E, 32);
;             const float P0 = g ? Po : Pp, E0 = g ? Eo : E, P1 = g ? Pp : Po, E1 = g ? E : Eo;
;             if (g == 0) { AGG[(wid * 2 + 0) * 32 + nl] = P0 * P1; AGG[(wid * 2 + 1) * 32 + nl] = fmaf(P1, E0, E1); }
	v_fma_f32 v244, -v32, v32, 1.0
	v_fma_f32 v245, -v33, v33, 1.0
	v_fma_f32 v246, -v34, v34, 1.0
	v_fma_f32 v247, -v35, v35, 1.0
	v_sqrt_f32_e32 v244, v244
	v_sqrt_f32_e32 v245, v245
	v_sqrt_f32_e32 v246, v246
	v_sqrt_f32_e32 v247, v247
	v_lshlrev_b32_e32 v162, 16, v162
	v_lshlrev_b32_e32 v163, 16, v163
	v_lshlrev_b32_e32 v232, 16, v232
	v_lshlrev_b32_e32 v233, 16, v233
	v_mul_f32_e32 v244, v244, v48
	v_mul_f32_e32 v245, v245, v49
	v_mul_f32_e32 v246, v246, v50
	v_mul_f32_e32 v247, v247, v51
	v_mul_f32_e32 v49, v244, v162
	v_mul_f32_e32 v228, v245, v163
	v_mul_f32_e32 v229, v246, v232
	v_mul_f32_e32 v230, v247, v233
	v_fma_f32 v244, -v36, v36, 1.0
	v_fma_f32 v245, -v37, v37, 1.0
	v_fma_f32 v246, -v38, v38, 1.0
	v_fma_f32 v247, -v39, v39, 1.0
	v_sqrt_f32_e32 v244, v244
	v_sqrt_f32_e32 v245, v245
	v_sqrt_f32_e32 v246, v246
	v_sqrt_f32_e32 v247, v247
	v_lshlrev_b32_e32 v234, 16, v234
	v_lshlrev_b32_e32 v235, 16, v235
	v_lshlrev_b32_e32 v236, 16, v236
	v_lshlrev_b32_e32 v237, 16, v237
	v_mul_f32_e32 v244, v244, v52
	v_mul_f32_e32 v245, v245, v53
	v_mul_f32_e32 v246, v246, v54
	v_mul_f32_e32 v247, v247, v55
	v_mul_f32_e32 v231, v244, v234
	v_mul_f32_e32 v232, v245, v235
	v_mul_f32_e32 v233, v246, v236
	v_mul_f32_e32 v234, v247, v237
	v_fma_f32 v244, -v40, v40, 1.0
	v_fma_f32 v245, -v41, v41, 1.0
	v_fma_f32 v246, -v42, v42, 1.0
	v_fma_f32 v247, -v43, v43, 1.0
	v_sqrt_f32_e32 v244, v244
	v_sqrt_f32_e32 v245, v245
	v_sqrt_f32_e32 v246, v246
	v_sqrt_f32_e32 v247, v247
	v_lshlrev_b32_e32 v146, 16, v146
	v_lshlrev_b32_e32 v147, 16, v147
	v_lshlrev_b32_e32 v148, 16, v148
	v_lshlrev_b32_e32 v149, 16, v149
	v_mul_f32_e32 v244, v244, v56
	v_mul_f32_e32 v245, v245, v57
	v_mul_f32_e32 v246, v246, v58
	v_mul_f32_e32 v247, v247, v59
	v_mul_f32_e32 v235, v244, v146
	v_mul_f32_e32 v236, v245, v147
	v_mul_f32_e32 v237, v246, v148
	v_mul_f32_e32 v238, v247, v149
	v_fma_f32 v244, -v44, v44, 1.0
	v_fma_f32 v245, -v45, v45, 1.0
	v_fma_f32 v246, -v46, v46, 1.0
	v_fma_f32 v247, -v47, v47, 1.0
	v_sqrt_f32_e32 v244, v244
	v_sqrt_f32_e32 v245, v245
	v_sqrt_f32_e32 v246, v246
	v_sqrt_f32_e32 v247, v247
	v_lshlrev_b32_e32 v239, 16, v239
	v_lshlrev_b32_e32 v240, 16, v240
	v_lshlrev_b32_e32 v241, 16, v241
	v_lshlrev_b32_e32 v242, 16, v242
	v_mul_f32_e32 v244, v244, v60
	v_mul_f32_e32 v245, v245, v61
	v_mul_f32_e32 v246, v246, v62
	v_mul_f32_e32 v247, v247, v63
	v_mul_f32_e32 v239, v244, v239
	v_mul_f32_e32 v240, v245, v240
	v_mul_f32_e32 v63, v246, v241
	v_mul_f32_e32 v241, v247, v242
	v_mov_b32_e32 v227, v32
	v_fmac_f32_e32 v49, 0, v32
	v_fmac_f32_e32 v228, v33, v49
	v_mul_f32_e32 v50, v227, v33
	v_fmac_f32_e32 v229, v34, v228
	v_mul_f32_e32 v51, v50, v34
	v_fmac_f32_e32 v230, v35, v229
	v_mul_f32_e32 v52, v51, v35
	v_fmac_f32_e32 v231, v36, v230
	v_mul_f32_e32 v53, v52, v36
	v_fmac_f32_e32 v232, v37, v231
	v_mul_f32_e32 v54, v53, v37
	v_fmac_f32_e32 v233, v38, v232
	v_mul_f32_e32 v55, v54, v38
	v_fmac_f32_e32 v234, v39, v233
	v_mul_f32_e32 v56, v55, v39
	v_fmac_f32_e32 v235, v40, v234
	v_mul_f32_e32 v57, v56, v40
	v_fmac_f32_e32 v236, v41, v235
	v_mul_f32_e32 v58, v57, v41
	v_fmac_f32_e32 v237, v42, v236
	v_mul_f32_e32 v59, v58, v42
	v_fmac_f32_e32 v238, v43, v237
	v_mul_f32_e32 v60, v59, v43
	v_fmac_f32_e32 v239, v44, v238
	v_mul_f32_e32 v61, v60, v44
	v_fmac_f32_e32 v240, v45, v239
	v_mul_f32_e32 v62, v61, v45
	v_fmac_f32_e32 v63, v46, v240
	v_mul_f32_e32 v243, v62, v46
	v_fmac_f32_e32 v241, v47, v63
	v_mul_f32_e32 v242, v243, v47
	ds_bpermute_b32 v244, v157, v242
	ds_bpermute_b32 v245, v157, v241
	s_and_saveexec_b64 s[18:19], vcc
	s_cbranch_execz .LBB0_313
	s_waitcnt lgkmcnt(0)
	v_fma_f32 v32, v244, v241, v245
	v_mul_f32_e32 v33, v242, v244
	v_add_u32_e32 v35, s98, v254
	ds_write2_b32 v35, v33, v32 offset1:32
; #define LAS __attribute__((address_space(3)))
; __device__ __forceinline__ unsigned cvt_pk_bf16(float lo, float hi) { unsigned r; asm volatile("v_cvt_pk_bf16_f32 %0, %1, %2" : "=v"(r) : "v"(lo), "v"(hi)); return r; }
; __device__ __forceinline__ float bf_lo(unsigned u) { return __uint_as_float(u << 16); }
; __device__ __forceinline__ float bf_hi(unsigned u) { return __uint_as_float(u & 0xffff0000u); }
; __device__ __forceinline__ bf16_t f2bf(float f) { return (bf16_t)(cvt_pk_bf16(f, 0.f) & 0xffffu); }
; #define LDS_BARRIER() do { asm volatile("s_waitcnt lgkmcnt(0)" ::: "memory"); __builtin_amdgcn_s_barrier(); asm volatile("" ::: "memory"); } while (0)
; template <int dir>
; __device__ __forceinline__ void lru_pass(LAS unsigned char* lds, const Params& P, int b, int h, int q, bool dry) {
;     ...
;             LDS_BARRIER();
;             float cin = carry, cend = carry;
; #pragma unroll
;             for (int w = 0; w < 8; ++w) { const float pw = AGG[(w * 2 + 0) * 32 + nl], ew = AGG[(w * 2 + 1) * 32 + nl]; if (w == wid) cin = cend; cend = fmaf(pw, cend, ew); }
;             carry = cend;
;             if (g) cin = fmaf(P0, cin, E0);
;             if (!isctx) {
; #pragma unroll
;                 for (int v = 0; v < 16; ++v) { const float hv = fmaf(zi[v], cin, zr[v]);
;                     const int s = sbase + v; const int tl = dir == 0 ? s : 255 - s;
;                     if (dir == 0) *(LAS unsigned*)(TOUT + tl * IO_WP + nl * 4) = (cvt_pk_bf16(hv, 0.f) & 0xffffu) | (pk[v] << 16);
;                     else *(LAS bf16_t*)(TOUT + tl * IO_NP + nl * 2) = f2bf((bf_lo(pk[v]) + hv) * bf_hi(pk[v])); }
.LBB0_313:
	s_or_b64 exec, exec, s[18:19]
	s_waitcnt lgkmcnt(0)
	s_barrier
	s_setprio 1
	v_add_u32_e32 v34, s99, v161
	ds_read2_b32 v[36:37], v34 offset1:32
	ds_read2_b32 v[38:39], v34 offset0:64 offset1:96
	ds_read2_b32 v[40:41], v34 offset0:128 offset1:160
	ds_read2_b32 v[42:43], v34 offset0:192 offset1:224
	v_add_u32_e32 v32, s100, v161
	s_waitcnt lgkmcnt(3)
	v_fmac_f32_e32 v37, v36, v222
	s_waitcnt lgkmcnt(2)
	v_fmac_f32_e32 v39, v38, v37
	s_waitcnt lgkmcnt(1)
	v_fmac_f32_e32 v41, v40, v39
	ds_read2_b32 v[44:45], v32 offset1:32
	ds_read2_b32 v[46:47], v32 offset0:64 offset1:96
	ds_read2_b32 v[34:35], v32 offset0:128 offset1:160
	ds_read2_b32 v[32:33], v32 offset0:192 offset1:224
	s_waitcnt lgkmcnt(4)
	v_fmac_f32_e32 v43, v42, v41
	s_waitcnt lgkmcnt(3)
	v_fmac_f32_e32 v45, v44, v43
	s_waitcnt lgkmcnt(2)
	v_fmac_f32_e32 v47, v46, v45
	s_cmp_eq_u32 s44, 0
	s_waitcnt lgkmcnt(1)
	v_fmac_f32_e32 v35, v34, v47
	s_cbranch_scc1 .LBB0_315
	v_cndmask_b32_e64 v37, v222, v37, s[14:15]
	v_cndmask_b32_e64 v37, v37, v39, s[12:13]
	v_cndmask_b32_e64 v37, v37, v41, s[10:11]
	v_cndmask_b32_e64 v37, v37, v43, s[8:9]
	v_cndmask_b32_e64 v37, v37, v45, s[4:5]
	v_cndmask_b32_e64 v37, v37, v47, s[16:17]
	v_cndmask_b32_e32 v34, v244, v242, vcc
	v_cndmask_b32_e32 v36, v245, v241, vcc
	v_cndmask_b32_e64 v37, v37, v35, s[0:1]
	v_fmac_f32_e32 v36, v34, v37
	v_cndmask_b32_e32 v34, v36, v37, vcc
	v_fmac_f32_e32 v49, v227, v34
	v_fmac_f32_e32 v228, v50, v34
	v_fmac_f32_e32 v229, v51, v34
	v_fmac_f32_e32 v230, v52, v34
	v_fmac_f32_e32 v231, v53, v34
	v_fmac_f32_e32 v232, v54, v34
	v_fmac_f32_e32 v233, v55, v34
	v_fmac_f32_e32 v234, v56, v34
	v_fmac_f32_e32 v235, v57, v34
	v_fmac_f32_e32 v236, v58, v34
	v_fmac_f32_e32 v237, v59, v34
	v_fmac_f32_e32 v238, v60, v34
	v_fmac_f32_e32 v239, v61, v34
	v_fmac_f32_e32 v240, v62, v34
	v_fmac_f32_e32 v63, v243, v34
	v_fmac_f32_e32 v241, v242, v34
	v_lshlrev_b32_e32 v36, 16, v226
	v_lshlrev_b32_e32 v38, 16, v225
	v_add_f32_e32 v36, v49, v36
	v_add_f32_e32 v38, v228, v38
	v_and_b32_e32 v37, 0xffff0000, v226
	v_and_b32_e32 v39, 0xffff0000, v225
	v_mul_f32_e32 v36, v36, v37
	v_mul_f32_e32 v38, v38, v39
	v_cvt_pk_bf16_f32 v36, v36, v38
	ds_write_b16 v206, v36
	ds_write_b16_d16_hi v207, v36
	v_lshlrev_b32_e32 v40, 16, v224
	v_lshlrev_b32_e32 v42, 16, v223
	v_add_f32_e32 v40, v229, v40
	v_add_f32_e32 v42, v230, v42
	v_and_b32_e32 v41, 0xffff0000, v224
	v_and_b32_e32 v43, 0xffff0000, v223
	v_mul_f32_e32 v40, v40, v41
	v_mul_f32_e32 v42, v42, v43
	v_cvt_pk_bf16_f32 v40, v40, v42
	ds_write_b16 v208, v40
	ds_write_b16_d16_hi v209, v40
	v_lshlrev_b32_e32 v36, 16, v135
	v_lshlrev_b32_e32 v38, 16, v134
	v_add_f32_e32 v36, v231, v36
	v_add_f32_e32 v38, v232, v38
	v_and_b32_e32 v37, 0xffff0000, v135
	v_and_b32_e32 v39, 0xffff0000, v134
	v_mul_f32_e32 v36, v36, v37
	v_mul_f32_e32 v38, v38, v39
	v_cvt_pk_bf16_f32 v36, v36, v38
	ds_write_b16 v210, v36
	ds_write_b16_d16_hi v211, v36
	v_lshlrev_b32_e32 v40, 16, v133
	v_lshlrev_b32_e32 v42, 16, v131
	v_add_f32_e32 v40, v233, v40
	v_add_f32_e32 v42, v234, v42
	v_and_b32_e32 v41, 0xffff0000, v133
	v_and_b32_e32 v43, 0xffff0000, v131
	v_mul_f32_e32 v40, v40, v41
	v_mul_f32_e32 v42, v42, v43
	v_cvt_pk_bf16_f32 v40, v40, v42
	ds_write_b16 v212, v40
	ds_write_b16_d16_hi v213, v40
	v_lshlrev_b32_e32 v36, 16, v132
	v_lshlrev_b32_e32 v38, 16, v130
	v_add_f32_e32 v36, v235, v36
	v_add_f32_e32 v38, v236, v38
	v_and_b32_e32 v37, 0xffff0000, v132
	v_and_b32_e32 v39, 0xffff0000, v130
	v_mul_f32_e32 v36, v36, v37
	v_mul_f32_e32 v38, v38, v39
	v_cvt_pk_bf16_f32 v36, v36, v38
	ds_write_b16 v214, v36
	ds_write_b16_d16_hi v215, v36
	v_lshlrev_b32_e32 v40, 16, v129
	v_lshlrev_b32_e32 v42, 16, v128
	v_add_f32_e32 v40, v237, v40
	v_add_f32_e32 v42, v238, v42
	v_and_b32_e32 v41, 0xffff0000, v129
	v_and_b32_e32 v43, 0xffff0000, v128
	v_mul_f32_e32 v40, v40, v41
	v_mul_f32_e32 v42, v42, v43
	v_cvt_pk_bf16_f32 v40, v40, v42
	ds_write_b16 v216, v40
	ds_write_b16_d16_hi v217, v40
	v_lshlrev_b32_e32 v36, 16, v67
	v_lshlrev_b32_e32 v38, 16, v66
	v_add_f32_e32 v36, v239, v36
	v_add_f32_e32 v38, v240, v38
	v_and_b32_e32 v37, 0xffff0000, v67
	v_and_b32_e32 v39, 0xffff0000, v66
	v_mul_f32_e32 v36, v36, v37
	v_mul_f32_e32 v38, v38, v39
	v_cvt_pk_bf16_f32 v36, v36, v38
	ds_write_b16 v218, v36
	ds_write_b16_d16_hi v219, v36
	v_lshlrev_b32_e32 v40, 16, v64
	v_lshlrev_b32_e32 v42, 16, v251
	v_add_f32_e32 v40, v63, v40
	v_add_f32_e32 v42, v241, v42
	v_and_b32_e32 v41, 0xffff0000, v64
	v_and_b32_e32 v43, 0xffff0000, v251
	v_mul_f32_e32 v40, v40, v41
	v_mul_f32_e32 v42, v42, v43
	v_cvt_pk_bf16_f32 v40, v40, v42
	ds_write_b16 v220, v40
	ds_write_b16_d16_hi v221, v40
